# lean SGPR-base re-encoding of the MB=3 K-loops of P5 and P9 (wave-half specialised copies, no per-stage mask branches), loop-control adds moved into the P8 load segment
# speedup vs baseline: 1.0148x; 1.0148x over previous
.LBB0_157:
	v_add_u32_e32 v140, s91, v180
	ds_read_b128 v[128:131], v140
	ds_read_b128 v[132:135], v140 offset:1024
	ds_read_b128 v[136:139], v140 offset:2048
	ds_read_b128 v[140:143], v140 offset:3072
	s_add_u32 s10, s8, 0xfff80080
	s_addc_u32 s11, s9, -1
	s_cmp_eq_u32 s74, 28
	s_cselect_b32 s73, s2, s11
	s_cselect_b32 s72, s13, s10
	s_cselect_b32 s11, s20, s71
	s_cselect_b32 s10, s63, s65
	s_add_i32 m0, s40, 0xc000
	ds_read_b128 v[144:147], v208
	ds_read_b128 v[172:175], v208 offset:1024
	ds_read_b128 v[176:179], v208 offset:2048
	ds_read_b128 v[212:215], v208 offset:3072
	global_load_lds_dwordx4 v166, s[8:9]
	s_add_i32 m0, s40, 0xe000
	ds_read_b128 v[216:219], v208 offset:4096
	ds_read_b128 v[220:223], v208 offset:5120
	ds_read_b128 v[224:227], v208 offset:6144
	ds_read_b128 v[228:231], v208 offset:7168
	global_load_lds_dwordx4 v168, s[8:9]
	s_waitcnt lgkmcnt(8)
	s_barrier
	s_waitcnt lgkmcnt(0)
	v_mfma_f32_16x16x32_bf16 v[124:127], v[128:131], v[144:147], v[124:127]
	v_mfma_f32_16x16x32_bf16 v[120:123], v[136:139], v[144:147], v[120:123]
	v_mfma_f32_16x16x32_bf16 v[108:111], v[128:131], v[176:179], v[108:111]
	v_mfma_f32_16x16x32_bf16 v[104:107], v[136:139], v[176:179], v[104:107]
	v_mfma_f32_16x16x32_bf16 v[92:95], v[128:131], v[216:219], v[92:95]
	v_mfma_f32_16x16x32_bf16 v[88:91], v[136:139], v[216:219], v[88:91]
	v_mfma_f32_16x16x32_bf16 v[76:79], v[128:131], v[224:227], v[76:79]
	v_mfma_f32_16x16x32_bf16 v[72:75], v[136:139], v[224:227], v[72:75]
	v_mfma_f32_16x16x32_bf16 v[124:127], v[132:135], v[172:175], v[124:127]
	v_mfma_f32_16x16x32_bf16 v[120:123], v[140:143], v[172:175], v[120:123]
	v_mfma_f32_16x16x32_bf16 v[108:111], v[132:135], v[212:215], v[108:111]
	v_mfma_f32_16x16x32_bf16 v[104:107], v[140:143], v[212:215], v[104:107]
	v_mfma_f32_16x16x32_bf16 v[92:95], v[132:135], v[220:223], v[92:95]
	v_mfma_f32_16x16x32_bf16 v[88:91], v[140:143], v[220:223], v[88:91]
	v_mfma_f32_16x16x32_bf16 v[76:79], v[132:135], v[228:231], v[76:79]
	v_mfma_f32_16x16x32_bf16 v[72:75], v[140:143], v[228:231], v[72:75]
	s_barrier
	v_add_u32_e32 v156, s92, v180
	s_add_i32 m0, s40, 0x10000
	ds_read_b128 v[232:235], v156
	ds_read_b128 v[236:239], v156 offset:1024
	global_load_lds_dwordx4 v150, s[10:11]
	s_add_i32 m0, s40, 0x12000
	ds_read_b128 v[240:243], v156 offset:2048
	ds_read_b128 v[244:247], v156 offset:3072
	global_load_lds_dwordx4 v154, s[10:11]
	s_barrier
	s_waitcnt lgkmcnt(0)
	v_mfma_f32_16x16x32_bf16 v[116:119], v[232:235], v[144:147], v[116:119]
	v_mfma_f32_16x16x32_bf16 v[112:115], v[240:243], v[144:147], v[112:115]
	v_mfma_f32_16x16x32_bf16 v[100:103], v[232:235], v[176:179], v[100:103]
	v_mfma_f32_16x16x32_bf16 v[96:99], v[240:243], v[176:179], v[96:99]
	v_mfma_f32_16x16x32_bf16 v[84:87], v[232:235], v[216:219], v[84:87]
	v_mfma_f32_16x16x32_bf16 v[80:83], v[240:243], v[216:219], v[80:83]
	v_mfma_f32_16x16x32_bf16 v[68:71], v[232:235], v[224:227], v[68:71]
	v_mfma_f32_16x16x32_bf16 v[64:67], v[240:243], v[224:227], v[64:67]
	v_mfma_f32_16x16x32_bf16 v[116:119], v[236:239], v[172:175], v[116:119]
	v_mfma_f32_16x16x32_bf16 v[112:115], v[244:247], v[172:175], v[112:115]
	v_mfma_f32_16x16x32_bf16 v[100:103], v[236:239], v[212:215], v[100:103]
	v_mfma_f32_16x16x32_bf16 v[96:99], v[244:247], v[212:215], v[96:99]
	v_mfma_f32_16x16x32_bf16 v[84:87], v[236:239], v[220:223], v[84:87]
	v_mfma_f32_16x16x32_bf16 v[80:83], v[244:247], v[220:223], v[80:83]
	v_mfma_f32_16x16x32_bf16 v[68:71], v[236:239], v[228:231], v[68:71]
	v_mfma_f32_16x16x32_bf16 v[64:67], v[244:247], v[228:231], v[64:67]
	s_barrier
	s_mov_b32 m0, s40
	ds_read_b128 v[144:147], v208 offset:16384
	ds_read_b128 v[172:175], v208 offset:17408
	ds_read_b128 v[176:179], v208 offset:18432
	ds_read_b128 v[212:215], v208 offset:19456
	global_load_lds_dwordx4 v148, s[72:73]
	s_mov_b32 m0, s41
	ds_read_b128 v[216:219], v208 offset:20480
	ds_read_b128 v[220:223], v208 offset:21504
	ds_read_b128 v[224:227], v208 offset:22528
	ds_read_b128 v[228:231], v208 offset:23552
	global_load_lds_dwordx4 v152, s[72:73]
	s_barrier
	s_waitcnt lgkmcnt(0)
	v_mfma_f32_16x16x32_bf16 v[60:63], v[128:131], v[144:147], v[60:63]
	v_mfma_f32_16x16x32_bf16 v[56:59], v[136:139], v[144:147], v[56:59]
	v_mfma_f32_16x16x32_bf16 v[44:47], v[128:131], v[176:179], v[44:47]
	v_mfma_f32_16x16x32_bf16 v[40:43], v[136:139], v[176:179], v[40:43]
	v_mfma_f32_16x16x32_bf16 v[28:31], v[128:131], v[216:219], v[28:31]
	v_mfma_f32_16x16x32_bf16 v[24:27], v[136:139], v[216:219], v[24:27]
	v_mfma_f32_16x16x32_bf16 v[12:15], v[128:131], v[224:227], v[12:15]
	v_mfma_f32_16x16x32_bf16 v[8:11], v[136:139], v[224:227], v[8:11]
	v_mfma_f32_16x16x32_bf16 v[60:63], v[132:135], v[172:175], v[60:63]
	v_mfma_f32_16x16x32_bf16 v[56:59], v[140:143], v[172:175], v[56:59]
	v_mfma_f32_16x16x32_bf16 v[44:47], v[132:135], v[212:215], v[44:47]
	v_mfma_f32_16x16x32_bf16 v[40:43], v[140:143], v[212:215], v[40:43]
	v_mfma_f32_16x16x32_bf16 v[28:31], v[132:135], v[220:223], v[28:31]
	v_mfma_f32_16x16x32_bf16 v[24:27], v[140:143], v[220:223], v[24:27]
	v_mfma_f32_16x16x32_bf16 v[12:15], v[132:135], v[228:231], v[12:15]
	v_mfma_f32_16x16x32_bf16 v[8:11], v[140:143], v[228:231], v[8:11]
	s_barrier
	s_add_u32 s34, s10, 0x80000
	s_addc_u32 s35, s11, 0
	s_add_i32 m0, s40, 0x14000
	s_nop 0
	global_load_lds_dwordx4 v150, s[34:35]
	s_add_i32 m0, s40, 0x16000
	s_nop 0
	global_load_lds_dwordx4 v154, s[34:35]
	s_waitcnt vmcnt(6)
	s_barrier
	v_mfma_f32_16x16x32_bf16 v[52:55], v[232:235], v[144:147], v[52:55]
	v_mfma_f32_16x16x32_bf16 v[48:51], v[240:243], v[144:147], v[48:51]
	v_mfma_f32_16x16x32_bf16 v[36:39], v[232:235], v[176:179], v[36:39]
	v_mfma_f32_16x16x32_bf16 v[32:35], v[240:243], v[176:179], v[32:35]
	v_mfma_f32_16x16x32_bf16 v[20:23], v[232:235], v[216:219], v[20:23]
	v_mfma_f32_16x16x32_bf16 v[16:19], v[240:243], v[216:219], v[16:19]
	v_mfma_f32_16x16x32_bf16 v[4:7], v[232:235], v[224:227], v[4:7]
	v_mfma_f32_16x16x32_bf16 v[0:3], v[240:243], v[224:227], v[0:3]
	v_mfma_f32_16x16x32_bf16 v[52:55], v[236:239], v[172:175], v[52:55]
	v_mfma_f32_16x16x32_bf16 v[48:51], v[244:247], v[172:175], v[48:51]
	v_mfma_f32_16x16x32_bf16 v[36:39], v[236:239], v[212:215], v[36:39]
	v_mfma_f32_16x16x32_bf16 v[32:35], v[244:247], v[212:215], v[32:35]
	v_mfma_f32_16x16x32_bf16 v[20:23], v[236:239], v[220:223], v[20:23]
	v_mfma_f32_16x16x32_bf16 v[16:19], v[244:247], v[220:223], v[16:19]
	v_mfma_f32_16x16x32_bf16 v[4:7], v[236:239], v[228:231], v[4:7]
	v_mfma_f32_16x16x32_bf16 v[0:3], v[244:247], v[228:231], v[0:3]
	s_barrier
	s_add_i32 s75, 0, 0x18000
	v_add_u32_e32 v140, s75, v180
	ds_read_b128 v[128:131], v140
	ds_read_b128 v[132:135], v140 offset:1024
	ds_read_b128 v[136:139], v140 offset:2048
	ds_read_b128 v[140:143], v140 offset:3072
	s_add_u32 s34, s72, 0x80000
	s_addc_u32 s35, s73, 0
	s_mov_b32 m0, s82
	ds_read_b128 v[144:147], v208 offset:32768
	ds_read_b128 v[172:175], v208 offset:33792
	ds_read_b128 v[176:179], v208 offset:34816
	ds_read_b128 v[212:215], v208 offset:35840
	global_load_lds_dwordx4 v148, s[34:35]
	s_mov_b32 m0, s83
	ds_read_b128 v[216:219], v208 offset:36864
	ds_read_b128 v[220:223], v208 offset:37888
	ds_read_b128 v[224:227], v208 offset:38912
	ds_read_b128 v[228:231], v208 offset:39936
	global_load_lds_dwordx4 v152, s[34:35]
	s_waitcnt lgkmcnt(8)
	s_barrier
	s_waitcnt lgkmcnt(0)
	v_mfma_f32_16x16x32_bf16 v[124:127], v[128:131], v[144:147], v[124:127]
	v_mfma_f32_16x16x32_bf16 v[120:123], v[136:139], v[144:147], v[120:123]
	v_mfma_f32_16x16x32_bf16 v[108:111], v[128:131], v[176:179], v[108:111]
	v_mfma_f32_16x16x32_bf16 v[104:107], v[136:139], v[176:179], v[104:107]
	v_mfma_f32_16x16x32_bf16 v[92:95], v[128:131], v[216:219], v[92:95]
	v_mfma_f32_16x16x32_bf16 v[88:91], v[136:139], v[216:219], v[88:91]
	v_mfma_f32_16x16x32_bf16 v[76:79], v[128:131], v[224:227], v[76:79]
	v_mfma_f32_16x16x32_bf16 v[72:75], v[136:139], v[224:227], v[72:75]
	v_mfma_f32_16x16x32_bf16 v[124:127], v[132:135], v[172:175], v[124:127]
	v_mfma_f32_16x16x32_bf16 v[120:123], v[140:143], v[172:175], v[120:123]
	v_mfma_f32_16x16x32_bf16 v[108:111], v[132:135], v[212:215], v[108:111]
	v_mfma_f32_16x16x32_bf16 v[104:107], v[140:143], v[212:215], v[104:107]
	v_mfma_f32_16x16x32_bf16 v[92:95], v[132:135], v[220:223], v[92:95]
	v_mfma_f32_16x16x32_bf16 v[88:91], v[140:143], v[220:223], v[88:91]
	v_mfma_f32_16x16x32_bf16 v[76:79], v[132:135], v[228:231], v[76:79]
	v_mfma_f32_16x16x32_bf16 v[72:75], v[140:143], v[228:231], v[72:75]
	s_barrier
	s_add_i32 s34, 0, 0x1c000
	v_add_u32_e32 v156, s34, v180
	s_add_u32 s34, s10, 0x80
	s_addc_u32 s35, s11, 0
	s_add_i32 m0, s40, 0x18000
	ds_read_b128 v[232:235], v156
	ds_read_b128 v[236:239], v156 offset:1024
	global_load_lds_dwordx4 v150, s[34:35]
	s_add_i32 m0, s40, 0x1a000
	ds_read_b128 v[240:243], v156 offset:2048
	ds_read_b128 v[244:247], v156 offset:3072
	global_load_lds_dwordx4 v154, s[34:35]
	s_barrier
	s_waitcnt lgkmcnt(0)
	v_mfma_f32_16x16x32_bf16 v[116:119], v[232:235], v[144:147], v[116:119]
	v_mfma_f32_16x16x32_bf16 v[112:115], v[240:243], v[144:147], v[112:115]
	v_mfma_f32_16x16x32_bf16 v[100:103], v[232:235], v[176:179], v[100:103]
	v_mfma_f32_16x16x32_bf16 v[96:99], v[240:243], v[176:179], v[96:99]
	v_mfma_f32_16x16x32_bf16 v[84:87], v[232:235], v[216:219], v[84:87]
	v_mfma_f32_16x16x32_bf16 v[80:83], v[240:243], v[216:219], v[80:83]
	v_mfma_f32_16x16x32_bf16 v[68:71], v[232:235], v[224:227], v[68:71]
	v_mfma_f32_16x16x32_bf16 v[64:67], v[240:243], v[224:227], v[64:67]
	v_mfma_f32_16x16x32_bf16 v[116:119], v[236:239], v[172:175], v[116:119]
	v_mfma_f32_16x16x32_bf16 v[112:115], v[244:247], v[172:175], v[112:115]
	v_mfma_f32_16x16x32_bf16 v[100:103], v[236:239], v[212:215], v[100:103]
	v_mfma_f32_16x16x32_bf16 v[96:99], v[244:247], v[212:215], v[96:99]
	v_mfma_f32_16x16x32_bf16 v[84:87], v[236:239], v[220:223], v[84:87]
	v_mfma_f32_16x16x32_bf16 v[80:83], v[244:247], v[220:223], v[80:83]
	v_mfma_f32_16x16x32_bf16 v[68:71], v[236:239], v[228:231], v[68:71]
	v_mfma_f32_16x16x32_bf16 v[64:67], v[244:247], v[228:231], v[64:67]
	s_barrier
	s_add_u32 s34, s72, 0x80
	s_addc_u32 s35, s73, 0
	s_mov_b32 m0, s87
	ds_read_b128 v[144:147], v208 offset:49152
	ds_read_b128 v[172:175], v208 offset:50176
	ds_read_b128 v[176:179], v208 offset:51200
	ds_read_b128 v[212:215], v208 offset:52224
	global_load_lds_dwordx4 v148, s[34:35]
	s_mov_b32 m0, s88
	ds_read_b128 v[216:219], v208 offset:53248
	ds_read_b128 v[220:223], v208 offset:54272
	ds_read_b128 v[224:227], v208 offset:55296
	ds_read_b128 v[228:231], v208 offset:56320
	global_load_lds_dwordx4 v152, s[34:35]
	s_barrier
	s_waitcnt lgkmcnt(0)
	v_mfma_f32_16x16x32_bf16 v[60:63], v[128:131], v[144:147], v[60:63]
	v_mfma_f32_16x16x32_bf16 v[56:59], v[136:139], v[144:147], v[56:59]
	v_mfma_f32_16x16x32_bf16 v[44:47], v[128:131], v[176:179], v[44:47]
	v_mfma_f32_16x16x32_bf16 v[40:43], v[136:139], v[176:179], v[40:43]
	v_mfma_f32_16x16x32_bf16 v[28:31], v[128:131], v[216:219], v[28:31]
	v_mfma_f32_16x16x32_bf16 v[24:27], v[136:139], v[216:219], v[24:27]
	v_mfma_f32_16x16x32_bf16 v[12:15], v[128:131], v[224:227], v[12:15]
	v_mfma_f32_16x16x32_bf16 v[8:11], v[136:139], v[224:227], v[8:11]
	v_mfma_f32_16x16x32_bf16 v[60:63], v[132:135], v[172:175], v[60:63]
	v_mfma_f32_16x16x32_bf16 v[56:59], v[140:143], v[172:175], v[56:59]
	v_mfma_f32_16x16x32_bf16 v[44:47], v[132:135], v[212:215], v[44:47]
	v_mfma_f32_16x16x32_bf16 v[40:43], v[140:143], v[212:215], v[40:43]
	v_mfma_f32_16x16x32_bf16 v[28:31], v[132:135], v[220:223], v[28:31]
	v_mfma_f32_16x16x32_bf16 v[24:27], v[140:143], v[220:223], v[24:27]
	v_mfma_f32_16x16x32_bf16 v[12:15], v[132:135], v[228:231], v[12:15]
	v_mfma_f32_16x16x32_bf16 v[8:11], v[140:143], v[228:231], v[8:11]
	s_barrier
	s_add_u32 s34, s10, 0x80080
	s_addc_u32 s35, s11, 0
	s_add_i32 m0, s40, 0x1c000
	s_add_i32 s74, s74, 2
	global_load_lds_dwordx4 v150, s[34:35]
	s_add_i32 m0, s40, 0x1e000
	s_nop 0
	global_load_lds_dwordx4 v154, s[34:35]
	s_add_u32 s8, s8, 0x100
	s_addc_u32 s9, s9, 0
	s_add_u32 s65, s65, 0x100
	s_addc_u32 s71, s71, 0
	s_waitcnt vmcnt(6)
	s_barrier
	v_mfma_f32_16x16x32_bf16 v[52:55], v[232:235], v[144:147], v[52:55]
	v_mfma_f32_16x16x32_bf16 v[48:51], v[240:243], v[144:147], v[48:51]
	v_mfma_f32_16x16x32_bf16 v[36:39], v[232:235], v[176:179], v[36:39]
	v_mfma_f32_16x16x32_bf16 v[32:35], v[240:243], v[176:179], v[32:35]
	v_mfma_f32_16x16x32_bf16 v[20:23], v[232:235], v[216:219], v[20:23]
	v_mfma_f32_16x16x32_bf16 v[16:19], v[240:243], v[216:219], v[16:19]
	v_mfma_f32_16x16x32_bf16 v[4:7], v[232:235], v[224:227], v[4:7]
	v_mfma_f32_16x16x32_bf16 v[0:3], v[240:243], v[224:227], v[0:3]
	v_mfma_f32_16x16x32_bf16 v[52:55], v[236:239], v[172:175], v[52:55]
	v_mfma_f32_16x16x32_bf16 v[48:51], v[244:247], v[172:175], v[48:51]
	v_mfma_f32_16x16x32_bf16 v[36:39], v[236:239], v[212:215], v[36:39]
	v_mfma_f32_16x16x32_bf16 v[32:35], v[244:247], v[212:215], v[32:35]
	v_mfma_f32_16x16x32_bf16 v[20:23], v[236:239], v[220:223], v[20:23]
	v_mfma_f32_16x16x32_bf16 v[16:19], v[244:247], v[220:223], v[16:19]
	v_mfma_f32_16x16x32_bf16 v[4:7], v[236:239], v[228:231], v[4:7]
	v_mfma_f32_16x16x32_bf16 v[0:3], v[244:247], v[228:231], v[0:3]
	s_cmp_gt_u32 s74, 29
	s_barrier
	s_cbranch_scc0 .LBB0_157
	s_cmp_gt_i32 s70, 15
	s_cselect_b64 s[74:75], -1, 0
	s_cmp_lt_i32 s70, 16
	s_cselect_b64 s[72:73], -1, 0
	s_cmp_gt_i32 s12, 9
	s_mov_b64 s[8:9], -1
	s_cbranch_scc0 .LBB0_338
	s_cmp_gt_u32 s12, 11
	s_cbranch_scc0 .LBB0_272
	s_cmp_gt_u32 s12, 19
	s_mov_b64 s[80:81], -1
	s_cbranch_scc0 .LBB0_173
	s_cmp_gt_u32 s12, 27
	s_cbranch_scc0 .LBB0_170
	s_lshl_b32 s2, s12, 8
	s_cmp_gt_u32 s12, 35
	s_mov_b64 s[8:9], -1
	s_mov_b64 s[78:79], -1
	s_cbranch_scc0 .LBB0_168
	s_cmp_gt_u32 s12, 43
	s_mov_b64 s[10:11], -1
	s_cbranch_scc0 .LBB0_165
	s_add_i32 s20, s2, 0xffffd400
	s_mov_b64 s[10:11], 0

.LBB0_829:
	s_and_b64 vcc, exec, s[4:5]
	s_cbranch_vccnz .Lq3_p5_one
	.p2align 7
.Lq3_p5_two:
	v_add_u32_e32 v1, 0x10000, v187
	ds_read_b128 v[100:103], v1
	ds_read_b128 v[104:107], v1 offset:1024
	ds_read_b128 v[108:111], v1 offset:2048
	ds_read_b128 v[112:115], v1 offset:3072
	s_add_i32 m0, s40, 0xc000
	ds_read_b128 v[148:151], v188
	ds_read_b128 v[152:155], v188 offset:1024
	ds_read_b128 v[140:143], v188 offset:2048
	global_load_lds_dwordx4 v166, s[46:47]
	s_add_i32 m0, s40, 0xe000
	ds_read_b128 v[144:147], v188 offset:3072
	ds_read_b128 v[132:135], v188 offset:4096
	ds_read_b128 v[136:139], v188 offset:5120
	global_load_lds_dwordx4 v168, s[46:47]
	s_add_u32 s30, s46, 0xfff40080
	s_addc_u32 s31, s47, -1
	s_cmp_eq_u32 s65, 28
	s_cselect_b32 s49, s25, s31
	s_cselect_b32 s48, s24, s30
	s_cselect_b32 s31, s7, s35
	s_cselect_b32 s30, s23, s34
	s_waitcnt lgkmcnt(8)
	s_barrier
	s_waitcnt lgkmcnt(0)
	v_mfma_f32_16x16x32_bf16 v[96:99], v[100:103], v[148:151], v[96:99]
	v_mfma_f32_16x16x32_bf16 v[92:95], v[108:111], v[148:151], v[92:95]
	v_mfma_f32_16x16x32_bf16 v[88:91], v[100:103], v[140:143], v[88:91]
	v_mfma_f32_16x16x32_bf16 v[84:87], v[108:111], v[140:143], v[84:87]
	v_mfma_f32_16x16x32_bf16 v[80:83], v[100:103], v[132:135], v[80:83]
	v_mfma_f32_16x16x32_bf16 v[76:79], v[108:111], v[132:135], v[76:79]
	v_mfma_f32_16x16x32_bf16 v[96:99], v[104:107], v[152:155], v[96:99]
	v_mfma_f32_16x16x32_bf16 v[92:95], v[112:115], v[152:155], v[92:95]
	v_mfma_f32_16x16x32_bf16 v[88:91], v[104:107], v[144:147], v[88:91]
	v_mfma_f32_16x16x32_bf16 v[84:87], v[112:115], v[144:147], v[84:87]
	v_mfma_f32_16x16x32_bf16 v[80:83], v[104:107], v[136:139], v[80:83]
	v_mfma_f32_16x16x32_bf16 v[76:79], v[112:115], v[136:139], v[76:79]
	s_barrier
	v_add_u32_e32 v1, 0x14000, v187
	s_mov_b32 m0, s41
	ds_read_b128 v[116:119], v1
	ds_read_b128 v[120:123], v1 offset:1024
	global_load_lds_dwordx4 v158, s[30:31]
	s_mov_b32 m0, s52
	ds_read_b128 v[124:127], v1 offset:2048
	ds_read_b128 v[128:131], v1 offset:3072
	global_load_lds_dwordx4 v160, s[30:31]
	s_barrier
	s_waitcnt lgkmcnt(0)
	v_mfma_f32_16x16x32_bf16 v[72:75], v[116:119], v[148:151], v[72:75]
	v_mfma_f32_16x16x32_bf16 v[68:71], v[124:127], v[148:151], v[68:71]
	v_mfma_f32_16x16x32_bf16 v[64:67], v[116:119], v[140:143], v[64:67]
	v_mfma_f32_16x16x32_bf16 v[60:63], v[124:127], v[140:143], v[60:63]
	v_mfma_f32_16x16x32_bf16 v[56:59], v[116:119], v[132:135], v[56:59]
	v_mfma_f32_16x16x32_bf16 v[52:55], v[124:127], v[132:135], v[52:55]
	v_mfma_f32_16x16x32_bf16 v[72:75], v[120:123], v[152:155], v[72:75]
	v_mfma_f32_16x16x32_bf16 v[68:71], v[128:131], v[152:155], v[68:71]
	v_mfma_f32_16x16x32_bf16 v[64:67], v[120:123], v[144:147], v[64:67]
	v_mfma_f32_16x16x32_bf16 v[60:63], v[128:131], v[144:147], v[60:63]
	v_mfma_f32_16x16x32_bf16 v[56:59], v[120:123], v[136:139], v[56:59]
	v_mfma_f32_16x16x32_bf16 v[52:55], v[128:131], v[136:139], v[52:55]
	s_barrier
	s_mov_b32 m0, s40
	ds_read_b128 v[148:151], v188 offset:16384
	ds_read_b128 v[152:155], v188 offset:17408
	ds_read_b128 v[140:143], v188 offset:18432
	global_load_lds_dwordx4 v156, s[48:49]
	s_add_i32 m0, s40, 0x2000
	ds_read_b128 v[144:147], v188 offset:19456
	ds_read_b128 v[132:135], v188 offset:20480
	ds_read_b128 v[136:139], v188 offset:21504
	global_load_lds_dwordx4 v162, s[48:49]
	s_barrier
	s_waitcnt lgkmcnt(0)
	v_mfma_f32_16x16x32_bf16 v[48:51], v[100:103], v[148:151], v[48:51]
	v_mfma_f32_16x16x32_bf16 v[44:47], v[108:111], v[148:151], v[44:47]
	v_mfma_f32_16x16x32_bf16 v[40:43], v[100:103], v[140:143], v[40:43]
	v_mfma_f32_16x16x32_bf16 v[36:39], v[108:111], v[140:143], v[36:39]
	v_mfma_f32_16x16x32_bf16 v[32:35], v[100:103], v[132:135], v[32:35]
	v_mfma_f32_16x16x32_bf16 v[28:31], v[108:111], v[132:135], v[28:31]
	v_mfma_f32_16x16x32_bf16 v[48:51], v[104:107], v[152:155], v[48:51]
	v_mfma_f32_16x16x32_bf16 v[44:47], v[112:115], v[152:155], v[44:47]
	v_mfma_f32_16x16x32_bf16 v[40:43], v[104:107], v[144:147], v[40:43]
	v_mfma_f32_16x16x32_bf16 v[36:39], v[112:115], v[144:147], v[36:39]
	v_mfma_f32_16x16x32_bf16 v[32:35], v[104:107], v[136:139], v[32:35]
	v_mfma_f32_16x16x32_bf16 v[28:31], v[112:115], v[136:139], v[28:31]
	s_barrier
	s_add_u32 s50, s30, 0x100000
	s_addc_u32 s51, s31, 0
	s_mov_b32 m0, s53
	s_nop 0
	global_load_lds_dwordx4 v158, s[50:51]
	s_mov_b32 m0, s54
	s_nop 0
	global_load_lds_dwordx4 v160, s[50:51]
	s_waitcnt vmcnt(6)
	s_barrier
	v_mfma_f32_16x16x32_bf16 v[24:27], v[116:119], v[148:151], v[24:27]
	v_mfma_f32_16x16x32_bf16 v[20:23], v[124:127], v[148:151], v[20:23]
	v_mfma_f32_16x16x32_bf16 v[16:19], v[116:119], v[140:143], v[16:19]
	v_mfma_f32_16x16x32_bf16 v[12:15], v[124:127], v[140:143], v[12:15]
	v_mfma_f32_16x16x32_bf16 v[8:11], v[116:119], v[132:135], v[8:11]
	v_mfma_f32_16x16x32_bf16 v[2:5], v[124:127], v[132:135], v[4:7]
	v_mfma_f32_16x16x32_bf16 v[24:27], v[120:123], v[152:155], v[24:27]
	v_mfma_f32_16x16x32_bf16 v[20:23], v[128:131], v[152:155], v[20:23]
	v_mfma_f32_16x16x32_bf16 v[16:19], v[120:123], v[144:147], v[16:19]
	v_mfma_f32_16x16x32_bf16 v[12:15], v[128:131], v[144:147], v[12:15]
	v_mfma_f32_16x16x32_bf16 v[8:11], v[120:123], v[136:139], v[8:11]
	v_mfma_f32_16x16x32_bf16 v[2:5], v[128:131], v[136:139], v[2:5]
	s_barrier
	v_add_u32_e32 v1, 0x18000, v187
	ds_read_b128 v[116:119], v1
	ds_read_b128 v[120:123], v1 offset:1024
	ds_read_b128 v[124:127], v1 offset:2048
	ds_read_b128 v[128:131], v1 offset:3072
	s_add_u32 s48, s48, 0xc0000
	s_addc_u32 s49, s49, 0
	s_mov_b32 m0, s55
	ds_read_b128 v[148:151], v188 offset:32768
	ds_read_b128 v[152:155], v188 offset:33792
	ds_read_b128 v[140:143], v188 offset:34816
	global_load_lds_dwordx4 v156, s[48:49]
	s_add_i32 m0, s40, 0x6000
	ds_read_b128 v[144:147], v188 offset:35840
	ds_read_b128 v[132:135], v188 offset:36864
	ds_read_b128 v[136:139], v188 offset:37888
	global_load_lds_dwordx4 v162, s[48:49]
	s_waitcnt lgkmcnt(8)
	s_barrier
	s_waitcnt lgkmcnt(0)
	v_mfma_f32_16x16x32_bf16 v[96:99], v[116:119], v[148:151], v[96:99]
	v_mfma_f32_16x16x32_bf16 v[92:95], v[124:127], v[148:151], v[92:95]
	v_mfma_f32_16x16x32_bf16 v[88:91], v[116:119], v[140:143], v[88:91]
	v_mfma_f32_16x16x32_bf16 v[84:87], v[124:127], v[140:143], v[84:87]
	v_mfma_f32_16x16x32_bf16 v[80:83], v[116:119], v[132:135], v[80:83]
	v_mfma_f32_16x16x32_bf16 v[76:79], v[124:127], v[132:135], v[76:79]
	v_mfma_f32_16x16x32_bf16 v[96:99], v[120:123], v[152:155], v[96:99]
	v_mfma_f32_16x16x32_bf16 v[92:95], v[128:131], v[152:155], v[92:95]
	v_mfma_f32_16x16x32_bf16 v[88:91], v[120:123], v[144:147], v[88:91]
	v_mfma_f32_16x16x32_bf16 v[84:87], v[128:131], v[144:147], v[84:87]
	v_mfma_f32_16x16x32_bf16 v[80:83], v[120:123], v[136:139], v[80:83]
	v_mfma_f32_16x16x32_bf16 v[76:79], v[128:131], v[136:139], v[76:79]
	s_barrier
	v_add_u32_e32 v1, 0x1c000, v187
	s_add_u32 s50, s30, 0x80
	s_addc_u32 s51, s31, 0
	s_mov_b32 m0, s56
	ds_read_b128 v[100:103], v1
	ds_read_b128 v[104:107], v1 offset:1024
	global_load_lds_dwordx4 v158, s[50:51]
	s_mov_b32 m0, s57
	ds_read_b128 v[108:111], v1 offset:2048
	ds_read_b128 v[112:115], v1 offset:3072
	global_load_lds_dwordx4 v160, s[50:51]
	s_barrier
	s_waitcnt lgkmcnt(0)
	v_mfma_f32_16x16x32_bf16 v[72:75], v[100:103], v[148:151], v[72:75]
	v_mfma_f32_16x16x32_bf16 v[68:71], v[108:111], v[148:151], v[68:71]
	v_mfma_f32_16x16x32_bf16 v[64:67], v[100:103], v[140:143], v[64:67]
	v_mfma_f32_16x16x32_bf16 v[60:63], v[108:111], v[140:143], v[60:63]
	v_mfma_f32_16x16x32_bf16 v[56:59], v[100:103], v[132:135], v[56:59]
	v_mfma_f32_16x16x32_bf16 v[52:55], v[108:111], v[132:135], v[52:55]
	v_mfma_f32_16x16x32_bf16 v[72:75], v[104:107], v[152:155], v[72:75]
	v_mfma_f32_16x16x32_bf16 v[68:71], v[112:115], v[152:155], v[68:71]
	v_mfma_f32_16x16x32_bf16 v[64:67], v[104:107], v[144:147], v[64:67]
	v_mfma_f32_16x16x32_bf16 v[60:63], v[112:115], v[144:147], v[60:63]
	v_mfma_f32_16x16x32_bf16 v[56:59], v[104:107], v[136:139], v[56:59]
	v_mfma_f32_16x16x32_bf16 v[52:55], v[112:115], v[136:139], v[52:55]
	s_barrier
	s_add_u32 s50, s48, 0xfff40080
	s_addc_u32 s51, s49, -1
	s_mov_b32 m0, s58
	ds_read_b128 v[148:151], v188 offset:49152
	ds_read_b128 v[152:155], v188 offset:50176
	ds_read_b128 v[140:143], v188 offset:51200
	global_load_lds_dwordx4 v156, s[50:51]
	s_add_i32 m0, s40, 0xa000
	ds_read_b128 v[144:147], v188 offset:52224
	ds_read_b128 v[132:135], v188 offset:53248
	ds_read_b128 v[136:139], v188 offset:54272
	global_load_lds_dwordx4 v162, s[50:51]
	s_barrier
	s_waitcnt lgkmcnt(0)
	v_mfma_f32_16x16x32_bf16 v[48:51], v[116:119], v[148:151], v[48:51]
	v_mfma_f32_16x16x32_bf16 v[44:47], v[124:127], v[148:151], v[44:47]
	v_mfma_f32_16x16x32_bf16 v[40:43], v[116:119], v[140:143], v[40:43]
	v_mfma_f32_16x16x32_bf16 v[36:39], v[124:127], v[140:143], v[36:39]
	v_mfma_f32_16x16x32_bf16 v[32:35], v[116:119], v[132:135], v[32:35]
	v_mfma_f32_16x16x32_bf16 v[28:31], v[124:127], v[132:135], v[28:31]
	v_mfma_f32_16x16x32_bf16 v[48:51], v[120:123], v[152:155], v[48:51]
	v_mfma_f32_16x16x32_bf16 v[44:47], v[128:131], v[152:155], v[44:47]
	v_mfma_f32_16x16x32_bf16 v[40:43], v[120:123], v[144:147], v[40:43]
	v_mfma_f32_16x16x32_bf16 v[36:39], v[128:131], v[144:147], v[36:39]
	v_mfma_f32_16x16x32_bf16 v[32:35], v[120:123], v[136:139], v[32:35]
	v_mfma_f32_16x16x32_bf16 v[28:31], v[128:131], v[136:139], v[28:31]
	s_barrier
	s_add_u32 s50, s30, 0x100080
	s_addc_u32 s51, s31, 0
	s_mov_b32 m0, s59
	s_add_i32 s65, s65, 2
	global_load_lds_dwordx4 v158, s[50:51]
	s_mov_b32 m0, s60
	s_nop 0
	global_load_lds_dwordx4 v160, s[50:51]
	s_add_u32 s46, s46, 0x100
	s_addc_u32 s47, s47, 0
	s_add_u32 s34, s34, 0x100
	s_addc_u32 s35, s35, 0
	s_waitcnt vmcnt(6)
	s_barrier
	v_mfma_f32_16x16x32_bf16 v[24:27], v[100:103], v[148:151], v[24:27]
	v_mfma_f32_16x16x32_bf16 v[20:23], v[108:111], v[148:151], v[20:23]
	v_mfma_f32_16x16x32_bf16 v[16:19], v[100:103], v[140:143], v[16:19]
	v_mfma_f32_16x16x32_bf16 v[12:15], v[108:111], v[140:143], v[12:15]
	v_mfma_f32_16x16x32_bf16 v[6:9], v[100:103], v[132:135], v[8:11]
	v_mfma_f32_16x16x32_bf16 v[2:5], v[108:111], v[132:135], v[2:5]
	v_mfma_f32_16x16x32_bf16 v[24:27], v[104:107], v[152:155], v[24:27]
	v_mfma_f32_16x16x32_bf16 v[20:23], v[112:115], v[152:155], v[20:23]
	v_mfma_f32_16x16x32_bf16 v[16:19], v[104:107], v[144:147], v[16:19]
	v_mfma_f32_16x16x32_bf16 v[12:15], v[112:115], v[144:147], v[12:15]
	v_mfma_f32_16x16x32_bf16 v[8:11], v[104:107], v[136:139], v[6:9]
	v_mfma_f32_16x16x32_bf16 v[4:7], v[112:115], v[136:139], v[2:5]
	s_cmp_gt_u32 s65, 29
	s_barrier
	s_cbranch_scc0 .Lq3_p5_two
	s_branch .LBB0_845
	.p2align 7
.Lq3_p5_one:
	v_add_u32_e32 v1, 0x10000, v187
	ds_read_b128 v[100:103], v1
	ds_read_b128 v[104:107], v1 offset:1024
	ds_read_b128 v[108:111], v1 offset:2048
	ds_read_b128 v[112:115], v1 offset:3072
	s_add_i32 m0, s40, 0xc000
	ds_read_b128 v[148:151], v188
	ds_read_b128 v[152:155], v188 offset:1024
	ds_read_b128 v[140:143], v188 offset:2048
	global_load_lds_dwordx4 v166, s[46:47]
	ds_read_b128 v[144:147], v188 offset:3072
	ds_read_b128 v[132:135], v188 offset:4096
	ds_read_b128 v[136:139], v188 offset:5120
	s_add_u32 s30, s46, 0xfff40080
	s_addc_u32 s31, s47, -1
	s_cmp_eq_u32 s65, 28
	s_cselect_b32 s49, s25, s31
	s_cselect_b32 s48, s24, s30
	s_cselect_b32 s31, s7, s35
	s_cselect_b32 s30, s23, s34
	s_waitcnt lgkmcnt(8)
	s_barrier
	s_waitcnt lgkmcnt(0)
	v_mfma_f32_16x16x32_bf16 v[96:99], v[100:103], v[148:151], v[96:99]
	v_mfma_f32_16x16x32_bf16 v[92:95], v[108:111], v[148:151], v[92:95]
	v_mfma_f32_16x16x32_bf16 v[88:91], v[100:103], v[140:143], v[88:91]
	v_mfma_f32_16x16x32_bf16 v[84:87], v[108:111], v[140:143], v[84:87]
	v_mfma_f32_16x16x32_bf16 v[80:83], v[100:103], v[132:135], v[80:83]
	v_mfma_f32_16x16x32_bf16 v[76:79], v[108:111], v[132:135], v[76:79]
	v_mfma_f32_16x16x32_bf16 v[96:99], v[104:107], v[152:155], v[96:99]
	v_mfma_f32_16x16x32_bf16 v[92:95], v[112:115], v[152:155], v[92:95]
	v_mfma_f32_16x16x32_bf16 v[88:91], v[104:107], v[144:147], v[88:91]
	v_mfma_f32_16x16x32_bf16 v[84:87], v[112:115], v[144:147], v[84:87]
	v_mfma_f32_16x16x32_bf16 v[80:83], v[104:107], v[136:139], v[80:83]
	v_mfma_f32_16x16x32_bf16 v[76:79], v[112:115], v[136:139], v[76:79]
	s_barrier
	v_add_u32_e32 v1, 0x14000, v187
	s_mov_b32 m0, s41
	ds_read_b128 v[116:119], v1
	ds_read_b128 v[120:123], v1 offset:1024
	global_load_lds_dwordx4 v158, s[30:31]
	s_mov_b32 m0, s52
	ds_read_b128 v[124:127], v1 offset:2048
	ds_read_b128 v[128:131], v1 offset:3072
	global_load_lds_dwordx4 v160, s[30:31]
	s_barrier
	s_waitcnt lgkmcnt(0)
	v_mfma_f32_16x16x32_bf16 v[72:75], v[116:119], v[148:151], v[72:75]
	v_mfma_f32_16x16x32_bf16 v[68:71], v[124:127], v[148:151], v[68:71]
	v_mfma_f32_16x16x32_bf16 v[64:67], v[116:119], v[140:143], v[64:67]
	v_mfma_f32_16x16x32_bf16 v[60:63], v[124:127], v[140:143], v[60:63]
	v_mfma_f32_16x16x32_bf16 v[56:59], v[116:119], v[132:135], v[56:59]
	v_mfma_f32_16x16x32_bf16 v[52:55], v[124:127], v[132:135], v[52:55]
	v_mfma_f32_16x16x32_bf16 v[72:75], v[120:123], v[152:155], v[72:75]
	v_mfma_f32_16x16x32_bf16 v[68:71], v[128:131], v[152:155], v[68:71]
	v_mfma_f32_16x16x32_bf16 v[64:67], v[120:123], v[144:147], v[64:67]
	v_mfma_f32_16x16x32_bf16 v[60:63], v[128:131], v[144:147], v[60:63]
	v_mfma_f32_16x16x32_bf16 v[56:59], v[120:123], v[136:139], v[56:59]
	v_mfma_f32_16x16x32_bf16 v[52:55], v[128:131], v[136:139], v[52:55]
	s_barrier
	s_mov_b32 m0, s40
	ds_read_b128 v[148:151], v188 offset:16384
	ds_read_b128 v[152:155], v188 offset:17408
	ds_read_b128 v[140:143], v188 offset:18432
	global_load_lds_dwordx4 v156, s[48:49]
	ds_read_b128 v[144:147], v188 offset:19456
	ds_read_b128 v[132:135], v188 offset:20480
	ds_read_b128 v[136:139], v188 offset:21504
	s_barrier
	s_waitcnt lgkmcnt(0)
	v_mfma_f32_16x16x32_bf16 v[48:51], v[100:103], v[148:151], v[48:51]
	v_mfma_f32_16x16x32_bf16 v[44:47], v[108:111], v[148:151], v[44:47]
	v_mfma_f32_16x16x32_bf16 v[40:43], v[100:103], v[140:143], v[40:43]
	v_mfma_f32_16x16x32_bf16 v[36:39], v[108:111], v[140:143], v[36:39]
	v_mfma_f32_16x16x32_bf16 v[32:35], v[100:103], v[132:135], v[32:35]
	v_mfma_f32_16x16x32_bf16 v[28:31], v[108:111], v[132:135], v[28:31]
	v_mfma_f32_16x16x32_bf16 v[48:51], v[104:107], v[152:155], v[48:51]
	v_mfma_f32_16x16x32_bf16 v[44:47], v[112:115], v[152:155], v[44:47]
	v_mfma_f32_16x16x32_bf16 v[40:43], v[104:107], v[144:147], v[40:43]
	v_mfma_f32_16x16x32_bf16 v[36:39], v[112:115], v[144:147], v[36:39]
	v_mfma_f32_16x16x32_bf16 v[32:35], v[104:107], v[136:139], v[32:35]
	v_mfma_f32_16x16x32_bf16 v[28:31], v[112:115], v[136:139], v[28:31]
	s_barrier
	s_add_u32 s50, s30, 0x100000
	s_addc_u32 s51, s31, 0
	s_mov_b32 m0, s53
	s_nop 0
	global_load_lds_dwordx4 v158, s[50:51]
	s_mov_b32 m0, s54
	s_nop 0
	global_load_lds_dwordx4 v160, s[50:51]
	s_waitcnt vmcnt(5)
	s_barrier
	v_mfma_f32_16x16x32_bf16 v[24:27], v[116:119], v[148:151], v[24:27]
	v_mfma_f32_16x16x32_bf16 v[20:23], v[124:127], v[148:151], v[20:23]
	v_mfma_f32_16x16x32_bf16 v[16:19], v[116:119], v[140:143], v[16:19]
	v_mfma_f32_16x16x32_bf16 v[12:15], v[124:127], v[140:143], v[12:15]
	v_mfma_f32_16x16x32_bf16 v[8:11], v[116:119], v[132:135], v[8:11]
	v_mfma_f32_16x16x32_bf16 v[2:5], v[124:127], v[132:135], v[4:7]
	v_mfma_f32_16x16x32_bf16 v[24:27], v[120:123], v[152:155], v[24:27]
	v_mfma_f32_16x16x32_bf16 v[20:23], v[128:131], v[152:155], v[20:23]
	v_mfma_f32_16x16x32_bf16 v[16:19], v[120:123], v[144:147], v[16:19]
	v_mfma_f32_16x16x32_bf16 v[12:15], v[128:131], v[144:147], v[12:15]
	v_mfma_f32_16x16x32_bf16 v[8:11], v[120:123], v[136:139], v[8:11]
	v_mfma_f32_16x16x32_bf16 v[2:5], v[128:131], v[136:139], v[2:5]
	s_barrier
	v_add_u32_e32 v1, 0x18000, v187
	ds_read_b128 v[116:119], v1
	ds_read_b128 v[120:123], v1 offset:1024
	ds_read_b128 v[124:127], v1 offset:2048
	ds_read_b128 v[128:131], v1 offset:3072
	s_add_u32 s48, s48, 0xc0000
	s_addc_u32 s49, s49, 0
	s_mov_b32 m0, s55
	ds_read_b128 v[148:151], v188 offset:32768
	ds_read_b128 v[152:155], v188 offset:33792
	ds_read_b128 v[140:143], v188 offset:34816
	global_load_lds_dwordx4 v156, s[48:49]
	ds_read_b128 v[144:147], v188 offset:35840
	ds_read_b128 v[132:135], v188 offset:36864
	ds_read_b128 v[136:139], v188 offset:37888
	s_waitcnt lgkmcnt(8)
	s_barrier
	s_waitcnt lgkmcnt(0)
	v_mfma_f32_16x16x32_bf16 v[96:99], v[116:119], v[148:151], v[96:99]
	v_mfma_f32_16x16x32_bf16 v[92:95], v[124:127], v[148:151], v[92:95]
	v_mfma_f32_16x16x32_bf16 v[88:91], v[116:119], v[140:143], v[88:91]
	v_mfma_f32_16x16x32_bf16 v[84:87], v[124:127], v[140:143], v[84:87]
	v_mfma_f32_16x16x32_bf16 v[80:83], v[116:119], v[132:135], v[80:83]
	v_mfma_f32_16x16x32_bf16 v[76:79], v[124:127], v[132:135], v[76:79]
	v_mfma_f32_16x16x32_bf16 v[96:99], v[120:123], v[152:155], v[96:99]
	v_mfma_f32_16x16x32_bf16 v[92:95], v[128:131], v[152:155], v[92:95]
	v_mfma_f32_16x16x32_bf16 v[88:91], v[120:123], v[144:147], v[88:91]
	v_mfma_f32_16x16x32_bf16 v[84:87], v[128:131], v[144:147], v[84:87]
	v_mfma_f32_16x16x32_bf16 v[80:83], v[120:123], v[136:139], v[80:83]
	v_mfma_f32_16x16x32_bf16 v[76:79], v[128:131], v[136:139], v[76:79]
	s_barrier
	v_add_u32_e32 v1, 0x1c000, v187
	s_add_u32 s50, s30, 0x80
	s_addc_u32 s51, s31, 0
	s_mov_b32 m0, s56
	ds_read_b128 v[100:103], v1
	ds_read_b128 v[104:107], v1 offset:1024
	global_load_lds_dwordx4 v158, s[50:51]
	s_mov_b32 m0, s57
	ds_read_b128 v[108:111], v1 offset:2048
	ds_read_b128 v[112:115], v1 offset:3072
	global_load_lds_dwordx4 v160, s[50:51]
	s_barrier
	s_waitcnt lgkmcnt(0)
	v_mfma_f32_16x16x32_bf16 v[72:75], v[100:103], v[148:151], v[72:75]
	v_mfma_f32_16x16x32_bf16 v[68:71], v[108:111], v[148:151], v[68:71]
	v_mfma_f32_16x16x32_bf16 v[64:67], v[100:103], v[140:143], v[64:67]
	v_mfma_f32_16x16x32_bf16 v[60:63], v[108:111], v[140:143], v[60:63]
	v_mfma_f32_16x16x32_bf16 v[56:59], v[100:103], v[132:135], v[56:59]
	v_mfma_f32_16x16x32_bf16 v[52:55], v[108:111], v[132:135], v[52:55]
	v_mfma_f32_16x16x32_bf16 v[72:75], v[104:107], v[152:155], v[72:75]
	v_mfma_f32_16x16x32_bf16 v[68:71], v[112:115], v[152:155], v[68:71]
	v_mfma_f32_16x16x32_bf16 v[64:67], v[104:107], v[144:147], v[64:67]
	v_mfma_f32_16x16x32_bf16 v[60:63], v[112:115], v[144:147], v[60:63]
	v_mfma_f32_16x16x32_bf16 v[56:59], v[104:107], v[136:139], v[56:59]
	v_mfma_f32_16x16x32_bf16 v[52:55], v[112:115], v[136:139], v[52:55]
	s_barrier
	s_add_u32 s50, s48, 0xfff40080
	s_addc_u32 s51, s49, -1
	s_mov_b32 m0, s58
	ds_read_b128 v[148:151], v188 offset:49152
	ds_read_b128 v[152:155], v188 offset:50176
	ds_read_b128 v[140:143], v188 offset:51200
	global_load_lds_dwordx4 v156, s[50:51]
	ds_read_b128 v[144:147], v188 offset:52224
	ds_read_b128 v[132:135], v188 offset:53248
	ds_read_b128 v[136:139], v188 offset:54272
	s_barrier
	s_waitcnt lgkmcnt(0)
	v_mfma_f32_16x16x32_bf16 v[48:51], v[116:119], v[148:151], v[48:51]
	v_mfma_f32_16x16x32_bf16 v[44:47], v[124:127], v[148:151], v[44:47]
	v_mfma_f32_16x16x32_bf16 v[40:43], v[116:119], v[140:143], v[40:43]
	v_mfma_f32_16x16x32_bf16 v[36:39], v[124:127], v[140:143], v[36:39]
	v_mfma_f32_16x16x32_bf16 v[32:35], v[116:119], v[132:135], v[32:35]
	v_mfma_f32_16x16x32_bf16 v[28:31], v[124:127], v[132:135], v[28:31]
	v_mfma_f32_16x16x32_bf16 v[48:51], v[120:123], v[152:155], v[48:51]
	v_mfma_f32_16x16x32_bf16 v[44:47], v[128:131], v[152:155], v[44:47]
	v_mfma_f32_16x16x32_bf16 v[40:43], v[120:123], v[144:147], v[40:43]
	v_mfma_f32_16x16x32_bf16 v[36:39], v[128:131], v[144:147], v[36:39]
	v_mfma_f32_16x16x32_bf16 v[32:35], v[120:123], v[136:139], v[32:35]
	v_mfma_f32_16x16x32_bf16 v[28:31], v[128:131], v[136:139], v[28:31]
	s_barrier
	s_add_u32 s50, s30, 0x100080
	s_addc_u32 s51, s31, 0
	s_mov_b32 m0, s59
	s_add_i32 s65, s65, 2
	global_load_lds_dwordx4 v158, s[50:51]
	s_mov_b32 m0, s60
	s_nop 0
	global_load_lds_dwordx4 v160, s[50:51]
	s_add_u32 s46, s46, 0x100
	s_addc_u32 s47, s47, 0
	s_add_u32 s34, s34, 0x100
	s_addc_u32 s35, s35, 0
	s_waitcnt vmcnt(5)
	s_barrier
	v_mfma_f32_16x16x32_bf16 v[24:27], v[100:103], v[148:151], v[24:27]
	v_mfma_f32_16x16x32_bf16 v[20:23], v[108:111], v[148:151], v[20:23]
	v_mfma_f32_16x16x32_bf16 v[16:19], v[100:103], v[140:143], v[16:19]
	v_mfma_f32_16x16x32_bf16 v[12:15], v[108:111], v[140:143], v[12:15]
	v_mfma_f32_16x16x32_bf16 v[6:9], v[100:103], v[132:135], v[8:11]
	v_mfma_f32_16x16x32_bf16 v[2:5], v[108:111], v[132:135], v[2:5]
	v_mfma_f32_16x16x32_bf16 v[24:27], v[104:107], v[152:155], v[24:27]
	v_mfma_f32_16x16x32_bf16 v[20:23], v[112:115], v[152:155], v[20:23]
	v_mfma_f32_16x16x32_bf16 v[16:19], v[104:107], v[144:147], v[16:19]
	v_mfma_f32_16x16x32_bf16 v[12:15], v[112:115], v[144:147], v[12:15]
	v_mfma_f32_16x16x32_bf16 v[8:11], v[104:107], v[136:139], v[6:9]
	v_mfma_f32_16x16x32_bf16 v[4:7], v[112:115], v[136:139], v[2:5]
	s_cmp_gt_u32 s65, 29
	s_barrier
	s_cbranch_scc0 .Lq3_p5_one

.LBB0_1065:
	ds_read_b128 v[152:155], v148
	ds_read_b128 v[156:159], v148 offset:1024
	ds_read_b128 v[160:163], v148 offset:2048
	ds_read_b128 v[164:167], v148 offset:3072
	s_add_u32 s28, s26, 0xfff80080
	s_addc_u32 s29, s27, -1
	s_cmp_eq_u32 s59, 28
	s_cselect_b32 s31, s15, s29
	s_cselect_b32 s30, s25, s28
	s_cselect_b32 s29, s17, s58
	s_cselect_b32 s28, s56, s57
	s_add_i32 m0, s47, 0xc000
	ds_read_b128 v[168:171], v149
	ds_read_b128 v[172:175], v149 offset:1024
	ds_read_b128 v[176:179], v149 offset:2048
	ds_read_b128 v[180:183], v149 offset:3072
	global_load_lds_dwordx4 v138, s[26:27]
	s_add_i32 m0, s47, 0xe000
	ds_read_b128 v[186:189], v149 offset:4096
	ds_read_b128 v[190:193], v149 offset:5120
	ds_read_b128 v[194:197], v149 offset:6144
	ds_read_b128 v[198:201], v149 offset:7168
	global_load_lds_dwordx4 v140, s[26:27]
	s_waitcnt lgkmcnt(8)
	s_barrier
	s_waitcnt lgkmcnt(0)
	v_mfma_f32_16x16x32_bf16 v[124:127], v[152:155], v[168:171], v[124:127]
	v_mfma_f32_16x16x32_bf16 v[120:123], v[160:163], v[168:171], v[120:123]
	v_mfma_f32_16x16x32_bf16 v[108:111], v[152:155], v[176:179], v[108:111]
	v_mfma_f32_16x16x32_bf16 v[104:107], v[160:163], v[176:179], v[104:107]
	v_mfma_f32_16x16x32_bf16 v[92:95], v[152:155], v[186:189], v[92:95]
	v_mfma_f32_16x16x32_bf16 v[88:91], v[160:163], v[186:189], v[88:91]
	v_mfma_f32_16x16x32_bf16 v[76:79], v[152:155], v[194:197], v[76:79]
	v_mfma_f32_16x16x32_bf16 v[72:75], v[160:163], v[194:197], v[72:75]
	v_mfma_f32_16x16x32_bf16 v[124:127], v[156:159], v[172:175], v[124:127]
	v_mfma_f32_16x16x32_bf16 v[120:123], v[164:167], v[172:175], v[120:123]
	v_mfma_f32_16x16x32_bf16 v[108:111], v[156:159], v[180:183], v[108:111]
	v_mfma_f32_16x16x32_bf16 v[104:107], v[164:167], v[180:183], v[104:107]
	v_mfma_f32_16x16x32_bf16 v[92:95], v[156:159], v[190:193], v[92:95]
	v_mfma_f32_16x16x32_bf16 v[88:91], v[164:167], v[190:193], v[88:91]
	v_mfma_f32_16x16x32_bf16 v[76:79], v[156:159], v[198:201], v[76:79]
	v_mfma_f32_16x16x32_bf16 v[72:75], v[164:167], v[198:201], v[72:75]
	s_barrier
	s_add_i32 m0, s47, 0x10000
	ds_read_b128 v[202:205], v150
	ds_read_b128 v[206:209], v150 offset:1024
	global_load_lds_dwordx4 v132, s[28:29]
	s_add_i32 m0, s47, 0x12000
	ds_read_b128 v[210:213], v150 offset:2048
	ds_read_b128 v[214:217], v150 offset:3072
	global_load_lds_dwordx4 v128, s[28:29]
	s_barrier
	s_waitcnt lgkmcnt(0)
	v_mfma_f32_16x16x32_bf16 v[116:119], v[202:205], v[168:171], v[116:119]
	v_mfma_f32_16x16x32_bf16 v[112:115], v[210:213], v[168:171], v[112:115]
	v_mfma_f32_16x16x32_bf16 v[100:103], v[202:205], v[176:179], v[100:103]
	v_mfma_f32_16x16x32_bf16 v[96:99], v[210:213], v[176:179], v[96:99]
	v_mfma_f32_16x16x32_bf16 v[84:87], v[202:205], v[186:189], v[84:87]
	v_mfma_f32_16x16x32_bf16 v[80:83], v[210:213], v[186:189], v[80:83]
	v_mfma_f32_16x16x32_bf16 v[68:71], v[202:205], v[194:197], v[68:71]
	v_mfma_f32_16x16x32_bf16 v[64:67], v[210:213], v[194:197], v[64:67]
	v_mfma_f32_16x16x32_bf16 v[116:119], v[206:209], v[172:175], v[116:119]
	v_mfma_f32_16x16x32_bf16 v[112:115], v[214:217], v[172:175], v[112:115]
	v_mfma_f32_16x16x32_bf16 v[100:103], v[206:209], v[180:183], v[100:103]
	v_mfma_f32_16x16x32_bf16 v[96:99], v[214:217], v[180:183], v[96:99]
	v_mfma_f32_16x16x32_bf16 v[84:87], v[206:209], v[190:193], v[84:87]
	v_mfma_f32_16x16x32_bf16 v[80:83], v[214:217], v[190:193], v[80:83]
	v_mfma_f32_16x16x32_bf16 v[68:71], v[206:209], v[198:201], v[68:71]
	v_mfma_f32_16x16x32_bf16 v[64:67], v[214:217], v[198:201], v[64:67]
	s_barrier
	s_mov_b32 m0, s47
	ds_read_b128 v[168:171], v149 offset:16384
	ds_read_b128 v[172:175], v149 offset:17408
	ds_read_b128 v[176:179], v149 offset:18432
	ds_read_b128 v[180:183], v149 offset:19456
	global_load_lds_dwordx4 v134, s[30:31]
	s_mov_b32 m0, s48
	ds_read_b128 v[186:189], v149 offset:20480
	ds_read_b128 v[190:193], v149 offset:21504
	ds_read_b128 v[194:197], v149 offset:22528
	ds_read_b128 v[198:201], v149 offset:23552
	global_load_lds_dwordx4 v130, s[30:31]
	s_barrier
	s_waitcnt lgkmcnt(0)
	v_mfma_f32_16x16x32_bf16 v[60:63], v[152:155], v[168:171], v[60:63]
	v_mfma_f32_16x16x32_bf16 v[56:59], v[160:163], v[168:171], v[56:59]
	v_mfma_f32_16x16x32_bf16 v[44:47], v[152:155], v[176:179], v[44:47]
	v_mfma_f32_16x16x32_bf16 v[40:43], v[160:163], v[176:179], v[40:43]
	v_mfma_f32_16x16x32_bf16 v[28:31], v[152:155], v[186:189], v[28:31]
	v_mfma_f32_16x16x32_bf16 v[24:27], v[160:163], v[186:189], v[24:27]
	v_mfma_f32_16x16x32_bf16 v[12:15], v[152:155], v[194:197], v[12:15]
	v_mfma_f32_16x16x32_bf16 v[8:11], v[160:163], v[194:197], v[8:11]
	v_mfma_f32_16x16x32_bf16 v[60:63], v[156:159], v[172:175], v[60:63]
	v_mfma_f32_16x16x32_bf16 v[56:59], v[164:167], v[172:175], v[56:59]
	v_mfma_f32_16x16x32_bf16 v[44:47], v[156:159], v[180:183], v[44:47]
	v_mfma_f32_16x16x32_bf16 v[40:43], v[164:167], v[180:183], v[40:43]
	v_mfma_f32_16x16x32_bf16 v[28:31], v[156:159], v[190:193], v[28:31]
	v_mfma_f32_16x16x32_bf16 v[24:27], v[164:167], v[190:193], v[24:27]
	v_mfma_f32_16x16x32_bf16 v[12:15], v[156:159], v[198:201], v[12:15]
	v_mfma_f32_16x16x32_bf16 v[8:11], v[164:167], v[198:201], v[8:11]
	s_barrier
	s_add_u32 s34, s28, 0x80000
	s_addc_u32 s35, s29, 0
	s_add_i32 m0, s47, 0x14000
	s_nop 0
	global_load_lds_dwordx4 v132, s[34:35]
	s_add_i32 m0, s47, 0x16000
	s_nop 0
	global_load_lds_dwordx4 v128, s[34:35]
	s_waitcnt vmcnt(6)
	s_barrier
	v_mfma_f32_16x16x32_bf16 v[52:55], v[202:205], v[168:171], v[52:55]
	v_mfma_f32_16x16x32_bf16 v[48:51], v[210:213], v[168:171], v[48:51]
	v_mfma_f32_16x16x32_bf16 v[36:39], v[202:205], v[176:179], v[36:39]
	v_mfma_f32_16x16x32_bf16 v[32:35], v[210:213], v[176:179], v[32:35]
	v_mfma_f32_16x16x32_bf16 v[20:23], v[202:205], v[186:189], v[20:23]
	v_mfma_f32_16x16x32_bf16 v[16:19], v[210:213], v[186:189], v[16:19]
	v_mfma_f32_16x16x32_bf16 v[4:7], v[202:205], v[194:197], v[4:7]
	v_mfma_f32_16x16x32_bf16 v[0:3], v[210:213], v[194:197], v[0:3]
	v_mfma_f32_16x16x32_bf16 v[52:55], v[206:209], v[172:175], v[52:55]
	v_mfma_f32_16x16x32_bf16 v[48:51], v[214:217], v[172:175], v[48:51]
	v_mfma_f32_16x16x32_bf16 v[36:39], v[206:209], v[180:183], v[36:39]
	v_mfma_f32_16x16x32_bf16 v[32:35], v[214:217], v[180:183], v[32:35]
	v_mfma_f32_16x16x32_bf16 v[20:23], v[206:209], v[190:193], v[20:23]
	v_mfma_f32_16x16x32_bf16 v[16:19], v[214:217], v[190:193], v[16:19]
	v_mfma_f32_16x16x32_bf16 v[4:7], v[206:209], v[198:201], v[4:7]
	v_mfma_f32_16x16x32_bf16 v[0:3], v[214:217], v[198:201], v[0:3]
	s_barrier
	s_add_i32 s34, 0, 0x18000
	v_add_u32_e32 v151, s34, v147
	ds_read_b128 v[152:155], v151
	ds_read_b128 v[156:159], v151 offset:1024
	ds_read_b128 v[160:163], v151 offset:2048
	ds_read_b128 v[164:167], v151 offset:3072
	s_add_u32 s34, s30, 0x80000
	s_addc_u32 s35, s31, 0
	s_mov_b32 m0, s49
	ds_read_b128 v[168:171], v149 offset:32768
	ds_read_b128 v[172:175], v149 offset:33792
	ds_read_b128 v[176:179], v149 offset:34816
	ds_read_b128 v[180:183], v149 offset:35840
	global_load_lds_dwordx4 v134, s[34:35]
	s_mov_b32 m0, s50
	ds_read_b128 v[186:189], v149 offset:36864
	ds_read_b128 v[190:193], v149 offset:37888
	ds_read_b128 v[194:197], v149 offset:38912
	ds_read_b128 v[198:201], v149 offset:39936
	global_load_lds_dwordx4 v130, s[34:35]
	s_waitcnt lgkmcnt(8)
	s_barrier
	s_waitcnt lgkmcnt(0)
	v_mfma_f32_16x16x32_bf16 v[124:127], v[152:155], v[168:171], v[124:127]
	v_mfma_f32_16x16x32_bf16 v[120:123], v[160:163], v[168:171], v[120:123]
	v_mfma_f32_16x16x32_bf16 v[108:111], v[152:155], v[176:179], v[108:111]
	v_mfma_f32_16x16x32_bf16 v[104:107], v[160:163], v[176:179], v[104:107]
	v_mfma_f32_16x16x32_bf16 v[92:95], v[152:155], v[186:189], v[92:95]
	v_mfma_f32_16x16x32_bf16 v[88:91], v[160:163], v[186:189], v[88:91]
	v_mfma_f32_16x16x32_bf16 v[76:79], v[152:155], v[194:197], v[76:79]
	v_mfma_f32_16x16x32_bf16 v[72:75], v[160:163], v[194:197], v[72:75]
	v_mfma_f32_16x16x32_bf16 v[124:127], v[156:159], v[172:175], v[124:127]
	v_mfma_f32_16x16x32_bf16 v[120:123], v[164:167], v[172:175], v[120:123]
	v_mfma_f32_16x16x32_bf16 v[108:111], v[156:159], v[180:183], v[108:111]
	v_mfma_f32_16x16x32_bf16 v[104:107], v[164:167], v[180:183], v[104:107]
	v_mfma_f32_16x16x32_bf16 v[92:95], v[156:159], v[190:193], v[92:95]
	v_mfma_f32_16x16x32_bf16 v[88:91], v[164:167], v[190:193], v[88:91]
	v_mfma_f32_16x16x32_bf16 v[76:79], v[156:159], v[198:201], v[76:79]
	v_mfma_f32_16x16x32_bf16 v[72:75], v[164:167], v[198:201], v[72:75]
	s_barrier
	s_add_i32 s34, 0, 0x1c000
	v_add_u32_e32 v151, s34, v147
	s_add_u32 s34, s28, 0x80
	s_addc_u32 s35, s29, 0
	s_add_i32 m0, s47, 0x18000
	ds_read_b128 v[202:205], v151
	ds_read_b128 v[206:209], v151 offset:1024
	global_load_lds_dwordx4 v132, s[34:35]
	s_add_i32 m0, s47, 0x1a000
	ds_read_b128 v[210:213], v151 offset:2048
	ds_read_b128 v[214:217], v151 offset:3072
	global_load_lds_dwordx4 v128, s[34:35]
	s_barrier
	s_waitcnt lgkmcnt(0)
	v_mfma_f32_16x16x32_bf16 v[116:119], v[202:205], v[168:171], v[116:119]
	v_mfma_f32_16x16x32_bf16 v[112:115], v[210:213], v[168:171], v[112:115]
	v_mfma_f32_16x16x32_bf16 v[100:103], v[202:205], v[176:179], v[100:103]
	v_mfma_f32_16x16x32_bf16 v[96:99], v[210:213], v[176:179], v[96:99]
	v_mfma_f32_16x16x32_bf16 v[84:87], v[202:205], v[186:189], v[84:87]
	v_mfma_f32_16x16x32_bf16 v[80:83], v[210:213], v[186:189], v[80:83]
	v_mfma_f32_16x16x32_bf16 v[68:71], v[202:205], v[194:197], v[68:71]
	v_mfma_f32_16x16x32_bf16 v[64:67], v[210:213], v[194:197], v[64:67]
	v_mfma_f32_16x16x32_bf16 v[116:119], v[206:209], v[172:175], v[116:119]
	v_mfma_f32_16x16x32_bf16 v[112:115], v[214:217], v[172:175], v[112:115]
	v_mfma_f32_16x16x32_bf16 v[100:103], v[206:209], v[180:183], v[100:103]
	v_mfma_f32_16x16x32_bf16 v[96:99], v[214:217], v[180:183], v[96:99]
	v_mfma_f32_16x16x32_bf16 v[84:87], v[206:209], v[190:193], v[84:87]
	v_mfma_f32_16x16x32_bf16 v[80:83], v[214:217], v[190:193], v[80:83]
	v_mfma_f32_16x16x32_bf16 v[68:71], v[206:209], v[198:201], v[68:71]
	v_mfma_f32_16x16x32_bf16 v[64:67], v[214:217], v[198:201], v[64:67]
	s_barrier
	s_add_u32 s34, s30, 0x80
	s_addc_u32 s35, s31, 0
	s_mov_b32 m0, s51
	ds_read_b128 v[168:171], v149 offset:49152
	ds_read_b128 v[172:175], v149 offset:50176
	ds_read_b128 v[176:179], v149 offset:51200
	ds_read_b128 v[180:183], v149 offset:52224
	global_load_lds_dwordx4 v134, s[34:35]
	s_mov_b32 m0, s52
	ds_read_b128 v[186:189], v149 offset:53248
	ds_read_b128 v[190:193], v149 offset:54272
	ds_read_b128 v[194:197], v149 offset:55296
	ds_read_b128 v[198:201], v149 offset:56320
	global_load_lds_dwordx4 v130, s[34:35]
	s_barrier
	s_waitcnt lgkmcnt(0)
	v_mfma_f32_16x16x32_bf16 v[60:63], v[152:155], v[168:171], v[60:63]
	v_mfma_f32_16x16x32_bf16 v[56:59], v[160:163], v[168:171], v[56:59]
	v_mfma_f32_16x16x32_bf16 v[44:47], v[152:155], v[176:179], v[44:47]
	v_mfma_f32_16x16x32_bf16 v[40:43], v[160:163], v[176:179], v[40:43]
	v_mfma_f32_16x16x32_bf16 v[28:31], v[152:155], v[186:189], v[28:31]
	v_mfma_f32_16x16x32_bf16 v[24:27], v[160:163], v[186:189], v[24:27]
	v_mfma_f32_16x16x32_bf16 v[12:15], v[152:155], v[194:197], v[12:15]
	v_mfma_f32_16x16x32_bf16 v[8:11], v[160:163], v[194:197], v[8:11]
	v_mfma_f32_16x16x32_bf16 v[60:63], v[156:159], v[172:175], v[60:63]
	v_mfma_f32_16x16x32_bf16 v[56:59], v[164:167], v[172:175], v[56:59]
	v_mfma_f32_16x16x32_bf16 v[44:47], v[156:159], v[180:183], v[44:47]
	v_mfma_f32_16x16x32_bf16 v[40:43], v[164:167], v[180:183], v[40:43]
	v_mfma_f32_16x16x32_bf16 v[28:31], v[156:159], v[190:193], v[28:31]
	v_mfma_f32_16x16x32_bf16 v[24:27], v[164:167], v[190:193], v[24:27]
	v_mfma_f32_16x16x32_bf16 v[12:15], v[156:159], v[198:201], v[12:15]
	v_mfma_f32_16x16x32_bf16 v[8:11], v[164:167], v[198:201], v[8:11]
	s_barrier
	s_add_u32 s34, s28, 0x80080
	s_addc_u32 s35, s29, 0
	s_add_i32 m0, s47, 0x1c000
	s_add_i32 s59, s59, 2
	global_load_lds_dwordx4 v132, s[34:35]
	s_add_i32 m0, s47, 0x1e000
	s_nop 0
	global_load_lds_dwordx4 v128, s[34:35]
	s_add_u32 s26, s26, 0x100
	s_addc_u32 s27, s27, 0
	s_add_u32 s57, s57, 0x100
	s_addc_u32 s58, s58, 0
	s_waitcnt vmcnt(6)
	s_barrier
	v_mfma_f32_16x16x32_bf16 v[52:55], v[202:205], v[168:171], v[52:55]
	v_mfma_f32_16x16x32_bf16 v[48:51], v[210:213], v[168:171], v[48:51]
	v_mfma_f32_16x16x32_bf16 v[36:39], v[202:205], v[176:179], v[36:39]
	v_mfma_f32_16x16x32_bf16 v[32:35], v[210:213], v[176:179], v[32:35]
	v_mfma_f32_16x16x32_bf16 v[20:23], v[202:205], v[186:189], v[20:23]
	v_mfma_f32_16x16x32_bf16 v[16:19], v[210:213], v[186:189], v[16:19]
	v_mfma_f32_16x16x32_bf16 v[4:7], v[202:205], v[194:197], v[4:7]
	v_mfma_f32_16x16x32_bf16 v[0:3], v[210:213], v[194:197], v[0:3]
	v_mfma_f32_16x16x32_bf16 v[52:55], v[206:209], v[172:175], v[52:55]
	v_mfma_f32_16x16x32_bf16 v[48:51], v[214:217], v[172:175], v[48:51]
	v_mfma_f32_16x16x32_bf16 v[36:39], v[206:209], v[180:183], v[36:39]
	v_mfma_f32_16x16x32_bf16 v[32:35], v[214:217], v[180:183], v[32:35]
	v_mfma_f32_16x16x32_bf16 v[20:23], v[206:209], v[190:193], v[20:23]
	v_mfma_f32_16x16x32_bf16 v[16:19], v[214:217], v[190:193], v[16:19]
	v_mfma_f32_16x16x32_bf16 v[4:7], v[206:209], v[198:201], v[4:7]
	v_mfma_f32_16x16x32_bf16 v[0:3], v[214:217], v[198:201], v[0:3]
	s_cmp_gt_u32 s59, 29
	s_barrier
	s_cbranch_scc0 .LBB0_1065
	v_mul_f32_e32 v154, 0xbfb8aa3b, v124
	v_exp_f32_e32 v154, v154
	v_mul_f32_e32 v155, 0xbfb8aa3b, v125
	v_exp_f32_e32 v155, v155
	v_lshl_add_u32 v151, s24, 8, v146
	v_add_f32_e32 v154, 1.0, v154
	v_rcp_f32_e32 v154, v154
	v_add_f32_e32 v155, 1.0, v155
	v_rcp_f32_e32 v155, v155
	s_lshl_b32 s24, s13, 7
	v_mul_f32_e32 v124, v124, v154
	v_mul_f32_e32 v120, v120, v124
	v_mul_f32_e32 v124, v125, v155
	v_mul_f32_e32 v125, 0xbfb8aa3b, v126
	v_exp_f32_e32 v125, v125
	v_mul_f32_e32 v154, 0xbfb8aa3b, v127
	v_exp_f32_e32 v154, v154
	v_mul_f32_e32 v121, v121, v124
	v_add_f32_e32 v124, 1.0, v125
	v_rcp_f32_e32 v124, v124
	v_add_f32_e32 v125, 1.0, v154
	v_rcp_f32_e32 v125, v125
	v_cvt_pk_bf16_f32 v120, v120, v121
	v_mul_f32_e32 v121, v126, v124
	v_mul_f32_e32 v121, v122, v121
	v_mul_f32_e32 v122, v127, v125
	v_mul_f32_e32 v122, v123, v122
	v_mul_f32_e32 v123, 0xbfb8aa3b, v116
	v_exp_f32_e32 v123, v123
	v_mul_f32_e32 v124, 0xbfb8aa3b, v117
	v_exp_f32_e32 v124, v124
	v_cvt_pk_bf16_f32 v121, v121, v122
	v_add_f32_e32 v122, 1.0, v123
	v_rcp_f32_e32 v122, v122
	v_add_f32_e32 v123, 1.0, v124
	s_ashr_i32 s25, s24, 31
	v_mov_b64_e32 v[144:145], s[6:7]
	v_rcp_f32_e32 v123, v123
	v_mad_i64_i32 v[152:153], s[26:27], v151, s55, v[144:145]
	s_lshl_b64 s[24:25], s[24:25], 1
	v_lshl_add_u64 v[152:153], v[152:153], 0, s[24:25]
	s_mov_b32 s13, s9
	v_lshl_add_u64 v[152:153], v[152:153], 0, s[12:13]
	v_mul_f32_e32 v116, v116, v122
	v_lshl_add_u64 v[152:153], v[152:153], 0, v[136:137]
	v_mul_f32_e32 v112, v112, v116
	v_mul_f32_e32 v116, v117, v123
	v_mul_f32_e32 v117, 0xbfb8aa3b, v118
	global_store_dwordx2 v[152:153], v[120:121], off
	v_exp_f32_e32 v117, v117
	v_mul_f32_e32 v120, 0xbfb8aa3b, v119
	v_exp_f32_e32 v120, v120
	v_mul_f32_e32 v113, v113, v116
	v_add_f32_e32 v116, 1.0, v117
	v_rcp_f32_e32 v116, v116
	v_add_f32_e32 v117, 1.0, v120
	v_rcp_f32_e32 v117, v117
	v_cvt_pk_bf16_f32 v112, v112, v113
	v_mul_f32_e32 v113, v118, v116
	v_mul_f32_e32 v113, v114, v113
	v_mul_f32_e32 v114, v119, v117
	v_mul_f32_e32 v114, v115, v114
	v_cvt_pk_bf16_f32 v113, v113, v114
	v_mul_f32_e32 v114, 0xbfb8aa3b, v108
	v_exp_f32_e32 v114, v114
	v_mul_f32_e32 v115, 0xbfb8aa3b, v109
	v_exp_f32_e32 v115, v115
	global_store_dwordx2 v[152:153], v[112:113], off offset:128
	v_add_f32_e32 v114, 1.0, v114
	v_rcp_f32_e32 v114, v114
	v_add_f32_e32 v115, 1.0, v115
	v_rcp_f32_e32 v115, v115
	v_or_b32_e32 v112, 16, v151
	v_mul_f32_e32 v108, v108, v114
	v_mul_f32_e32 v104, v104, v108
	v_mul_f32_e32 v108, v109, v115
	v_mul_f32_e32 v109, 0xbfb8aa3b, v110
	v_exp_f32_e32 v109, v109
	v_mul_f32_e32 v114, 0xbfb8aa3b, v111
	v_exp_f32_e32 v114, v114
	v_mul_f32_e32 v105, v105, v108
	v_add_f32_e32 v108, 1.0, v109
	v_rcp_f32_e32 v108, v108
	v_add_f32_e32 v109, 1.0, v114
	v_rcp_f32_e32 v109, v109
	v_cvt_pk_bf16_f32 v104, v104, v105
	v_mul_f32_e32 v105, v110, v108
	v_mul_f32_e32 v105, v106, v105
	v_mul_f32_e32 v106, v111, v109
	v_mul_f32_e32 v106, v107, v106
	v_mul_f32_e32 v107, 0xbfb8aa3b, v100
	v_exp_f32_e32 v107, v107
	v_mul_f32_e32 v108, 0xbfb8aa3b, v101
	v_exp_f32_e32 v108, v108
	v_cvt_pk_bf16_f32 v105, v105, v106
	v_add_f32_e32 v106, 1.0, v107
	v_rcp_f32_e32 v106, v106
	v_add_f32_e32 v107, 1.0, v108
	v_rcp_f32_e32 v107, v107
	v_mad_i64_i32 v[112:113], s[26:27], v112, s55, v[144:145]
	v_lshl_add_u64 v[112:113], v[112:113], 0, s[24:25]
	v_lshl_add_u64 v[112:113], v[112:113], 0, s[12:13]
	v_mul_f32_e32 v100, v100, v106
	v_lshl_add_u64 v[112:113], v[112:113], 0, v[136:137]
	v_mul_f32_e32 v96, v96, v100
	v_mul_f32_e32 v100, v101, v107
	v_mul_f32_e32 v101, 0xbfb8aa3b, v102
	global_store_dwordx2 v[112:113], v[104:105], off
	v_exp_f32_e32 v101, v101
	v_mul_f32_e32 v104, 0xbfb8aa3b, v103
	v_exp_f32_e32 v104, v104
	v_mul_f32_e32 v97, v97, v100
	v_add_f32_e32 v100, 1.0, v101
	v_rcp_f32_e32 v100, v100
	v_add_f32_e32 v101, 1.0, v104
	v_rcp_f32_e32 v101, v101
	v_cvt_pk_bf16_f32 v96, v96, v97
	v_mul_f32_e32 v97, v102, v100
	v_mul_f32_e32 v97, v98, v97
	v_mul_f32_e32 v98, v103, v101
	v_mul_f32_e32 v98, v99, v98
	v_cvt_pk_bf16_f32 v97, v97, v98
	v_mul_f32_e32 v98, 0xbfb8aa3b, v92
	v_exp_f32_e32 v98, v98
	v_mul_f32_e32 v99, 0xbfb8aa3b, v93
	v_exp_f32_e32 v99, v99
	global_store_dwordx2 v[112:113], v[96:97], off offset:128
	v_add_f32_e32 v98, 1.0, v98
	v_rcp_f32_e32 v98, v98
	v_add_f32_e32 v99, 1.0, v99
	v_rcp_f32_e32 v99, v99
	v_or_b32_e32 v96, 32, v151
	v_mul_f32_e32 v92, v92, v98
	v_mul_f32_e32 v88, v88, v92
	v_mul_f32_e32 v92, v93, v99
	v_mul_f32_e32 v93, 0xbfb8aa3b, v94
	v_exp_f32_e32 v93, v93
	v_mul_f32_e32 v98, 0xbfb8aa3b, v95
	v_exp_f32_e32 v98, v98
	v_mul_f32_e32 v89, v89, v92
	v_add_f32_e32 v92, 1.0, v93
	v_rcp_f32_e32 v92, v92
	v_add_f32_e32 v93, 1.0, v98
	v_rcp_f32_e32 v93, v93
	v_cvt_pk_bf16_f32 v88, v88, v89
	v_mul_f32_e32 v89, v94, v92
	v_mul_f32_e32 v89, v90, v89
	v_mul_f32_e32 v90, v95, v93
	v_mul_f32_e32 v90, v91, v90
	v_mul_f32_e32 v91, 0xbfb8aa3b, v84
	v_exp_f32_e32 v91, v91
	v_mul_f32_e32 v92, 0xbfb8aa3b, v85
	v_exp_f32_e32 v92, v92
	v_cvt_pk_bf16_f32 v89, v89, v90
	v_add_f32_e32 v90, 1.0, v91
	v_rcp_f32_e32 v90, v90
	v_add_f32_e32 v91, 1.0, v92
	v_rcp_f32_e32 v91, v91
	v_mad_i64_i32 v[96:97], s[26:27], v96, s55, v[144:145]
	v_lshl_add_u64 v[96:97], v[96:97], 0, s[24:25]
	v_lshl_add_u64 v[96:97], v[96:97], 0, s[12:13]
	v_mul_f32_e32 v84, v84, v90
	v_lshl_add_u64 v[96:97], v[96:97], 0, v[136:137]
	v_mul_f32_e32 v80, v80, v84
	v_mul_f32_e32 v84, v85, v91
	v_mul_f32_e32 v85, 0xbfb8aa3b, v86
	global_store_dwordx2 v[96:97], v[88:89], off
	v_exp_f32_e32 v85, v85
	v_mul_f32_e32 v88, 0xbfb8aa3b, v87
	v_exp_f32_e32 v88, v88
	v_mul_f32_e32 v81, v81, v84
	v_add_f32_e32 v84, 1.0, v85
	v_rcp_f32_e32 v84, v84
	v_add_f32_e32 v85, 1.0, v88
	v_rcp_f32_e32 v85, v85
	v_cvt_pk_bf16_f32 v80, v80, v81
	v_mul_f32_e32 v81, v86, v84
	v_mul_f32_e32 v81, v82, v81
	v_mul_f32_e32 v82, v87, v85
	v_mul_f32_e32 v82, v83, v82
	v_cvt_pk_bf16_f32 v81, v81, v82
	v_mul_f32_e32 v82, 0xbfb8aa3b, v76
	v_exp_f32_e32 v82, v82
	v_mul_f32_e32 v83, 0xbfb8aa3b, v77
	v_exp_f32_e32 v83, v83
	global_store_dwordx2 v[96:97], v[80:81], off offset:128
	v_add_f32_e32 v82, 1.0, v82
	v_rcp_f32_e32 v82, v82
	v_add_f32_e32 v83, 1.0, v83
	v_rcp_f32_e32 v83, v83
	v_or_b32_e32 v80, 48, v151
	v_mul_f32_e32 v76, v76, v82
	v_mul_f32_e32 v72, v72, v76
	v_mul_f32_e32 v76, v77, v83
	v_mul_f32_e32 v77, 0xbfb8aa3b, v78
	v_exp_f32_e32 v77, v77
	v_mul_f32_e32 v82, 0xbfb8aa3b, v79
	v_exp_f32_e32 v82, v82
	v_mul_f32_e32 v73, v73, v76
	v_add_f32_e32 v76, 1.0, v77
	v_rcp_f32_e32 v76, v76
	v_add_f32_e32 v77, 1.0, v82
	v_rcp_f32_e32 v77, v77
	v_cvt_pk_bf16_f32 v72, v72, v73
	v_mul_f32_e32 v73, v78, v76
	v_mul_f32_e32 v73, v74, v73
	v_mul_f32_e32 v74, v79, v77
	v_mul_f32_e32 v74, v75, v74
	v_mul_f32_e32 v75, 0xbfb8aa3b, v68
	v_exp_f32_e32 v75, v75
	v_mul_f32_e32 v76, 0xbfb8aa3b, v69
	v_exp_f32_e32 v76, v76
	v_cvt_pk_bf16_f32 v73, v73, v74
	v_add_f32_e32 v74, 1.0, v75
	v_rcp_f32_e32 v74, v74
	v_add_f32_e32 v75, 1.0, v76
	v_rcp_f32_e32 v75, v75
	v_mad_i64_i32 v[80:81], s[26:27], v80, s55, v[144:145]
	v_lshl_add_u64 v[80:81], v[80:81], 0, s[24:25]
	v_lshl_add_u64 v[80:81], v[80:81], 0, s[12:13]
	v_mul_f32_e32 v68, v68, v74
	v_lshl_add_u64 v[80:81], v[80:81], 0, v[136:137]
	v_mul_f32_e32 v64, v64, v68
	v_mul_f32_e32 v68, v69, v75
	v_mul_f32_e32 v69, 0xbfb8aa3b, v70
	global_store_dwordx2 v[80:81], v[72:73], off
	v_exp_f32_e32 v69, v69
	v_mul_f32_e32 v72, 0xbfb8aa3b, v71
	v_exp_f32_e32 v72, v72
	v_mul_f32_e32 v65, v65, v68
	v_add_f32_e32 v68, 1.0, v69
	v_rcp_f32_e32 v68, v68
	v_add_f32_e32 v69, 1.0, v72
	v_rcp_f32_e32 v69, v69
	v_cvt_pk_bf16_f32 v64, v64, v65
	v_mul_f32_e32 v65, v70, v68
	v_mul_f32_e32 v65, v66, v65
	v_mul_f32_e32 v66, v71, v69
	v_mul_f32_e32 v66, v67, v66
	v_cvt_pk_bf16_f32 v65, v65, v66
	v_mul_f32_e32 v66, 0xbfb8aa3b, v60
	v_exp_f32_e32 v66, v66
	v_mul_f32_e32 v67, 0xbfb8aa3b, v61
	v_exp_f32_e32 v67, v67
	global_store_dwordx2 v[80:81], v[64:65], off offset:128
	v_add_f32_e32 v66, 1.0, v66
	v_rcp_f32_e32 v66, v66
	v_add_f32_e32 v67, 1.0, v67
	v_rcp_f32_e32 v67, v67
	v_add_u32_e32 v64, 0x80, v151
	v_mul_f32_e32 v60, v60, v66
	v_mul_f32_e32 v56, v56, v60
	v_mul_f32_e32 v60, v61, v67
	v_mul_f32_e32 v61, 0xbfb8aa3b, v62
	v_exp_f32_e32 v61, v61
	v_mul_f32_e32 v66, 0xbfb8aa3b, v63
	v_exp_f32_e32 v66, v66
	v_mul_f32_e32 v57, v57, v60
	v_add_f32_e32 v60, 1.0, v61
	v_rcp_f32_e32 v60, v60
	v_add_f32_e32 v61, 1.0, v66
	v_rcp_f32_e32 v61, v61
	v_cvt_pk_bf16_f32 v56, v56, v57
	v_mul_f32_e32 v57, v62, v60
	v_mul_f32_e32 v57, v58, v57
	v_mul_f32_e32 v58, v63, v61
	v_mul_f32_e32 v58, v59, v58
	v_mul_f32_e32 v59, 0xbfb8aa3b, v52
	v_exp_f32_e32 v59, v59
	v_mul_f32_e32 v60, 0xbfb8aa3b, v53
	v_exp_f32_e32 v60, v60
	v_cvt_pk_bf16_f32 v57, v57, v58
	v_add_f32_e32 v58, 1.0, v59
	v_rcp_f32_e32 v58, v58
	v_add_f32_e32 v59, 1.0, v60
	v_rcp_f32_e32 v59, v59
	v_mad_i64_i32 v[64:65], s[26:27], v64, s55, v[144:145]
	v_lshl_add_u64 v[64:65], v[64:65], 0, s[24:25]
	v_lshl_add_u64 v[64:65], v[64:65], 0, s[12:13]
	v_mul_f32_e32 v52, v52, v58
	v_lshl_add_u64 v[64:65], v[64:65], 0, v[136:137]
	v_mul_f32_e32 v48, v48, v52
	v_mul_f32_e32 v52, v53, v59
	v_mul_f32_e32 v53, 0xbfb8aa3b, v54
	global_store_dwordx2 v[64:65], v[56:57], off
	v_exp_f32_e32 v53, v53
	v_mul_f32_e32 v56, 0xbfb8aa3b, v55
	v_exp_f32_e32 v56, v56
	v_mul_f32_e32 v49, v49, v52
	v_add_f32_e32 v52, 1.0, v53
	v_rcp_f32_e32 v52, v52
	v_add_f32_e32 v53, 1.0, v56
	v_rcp_f32_e32 v53, v53
	v_cvt_pk_bf16_f32 v48, v48, v49
	v_mul_f32_e32 v49, v54, v52
	v_mul_f32_e32 v49, v50, v49
	v_mul_f32_e32 v50, v55, v53
	v_mul_f32_e32 v50, v51, v50
	v_cvt_pk_bf16_f32 v49, v49, v50
	v_mul_f32_e32 v50, 0xbfb8aa3b, v44
	v_exp_f32_e32 v50, v50
	v_mul_f32_e32 v51, 0xbfb8aa3b, v45
	v_exp_f32_e32 v51, v51
	global_store_dwordx2 v[64:65], v[48:49], off offset:128
	v_add_f32_e32 v50, 1.0, v50
	v_rcp_f32_e32 v50, v50
	v_add_f32_e32 v51, 1.0, v51
	v_rcp_f32_e32 v51, v51
	v_add_u32_e32 v48, 0x90, v151
	v_mul_f32_e32 v44, v44, v50
	v_mul_f32_e32 v40, v40, v44
	v_mul_f32_e32 v44, v45, v51
	v_mul_f32_e32 v45, 0xbfb8aa3b, v46
	v_exp_f32_e32 v45, v45
	v_mul_f32_e32 v50, 0xbfb8aa3b, v47
	v_exp_f32_e32 v50, v50
	v_mul_f32_e32 v41, v41, v44
	v_add_f32_e32 v44, 1.0, v45
	v_rcp_f32_e32 v44, v44
	v_add_f32_e32 v45, 1.0, v50
	v_rcp_f32_e32 v45, v45
	v_cvt_pk_bf16_f32 v40, v40, v41
	v_mul_f32_e32 v41, v46, v44
	v_mul_f32_e32 v41, v42, v41
	v_mul_f32_e32 v42, v47, v45
	v_mul_f32_e32 v42, v43, v42
	v_mul_f32_e32 v43, 0xbfb8aa3b, v36
	v_exp_f32_e32 v43, v43
	v_mul_f32_e32 v44, 0xbfb8aa3b, v37
	v_exp_f32_e32 v44, v44
	v_cvt_pk_bf16_f32 v41, v41, v42
	v_add_f32_e32 v42, 1.0, v43
	v_rcp_f32_e32 v42, v42
	v_add_f32_e32 v43, 1.0, v44
	v_rcp_f32_e32 v43, v43
	v_mad_i64_i32 v[48:49], s[26:27], v48, s55, v[144:145]
	v_lshl_add_u64 v[48:49], v[48:49], 0, s[24:25]
	v_lshl_add_u64 v[48:49], v[48:49], 0, s[12:13]
	v_mul_f32_e32 v36, v36, v42
	v_lshl_add_u64 v[48:49], v[48:49], 0, v[136:137]
	v_mul_f32_e32 v32, v32, v36
	v_mul_f32_e32 v36, v37, v43
	v_mul_f32_e32 v37, 0xbfb8aa3b, v38
	global_store_dwordx2 v[48:49], v[40:41], off
	v_exp_f32_e32 v37, v37
	v_mul_f32_e32 v40, 0xbfb8aa3b, v39
	v_exp_f32_e32 v40, v40
	v_mul_f32_e32 v33, v33, v36
	v_add_f32_e32 v36, 1.0, v37
	v_rcp_f32_e32 v36, v36
	v_add_f32_e32 v37, 1.0, v40
	v_rcp_f32_e32 v37, v37
	v_cvt_pk_bf16_f32 v32, v32, v33
	v_mul_f32_e32 v33, v38, v36
	v_mul_f32_e32 v33, v34, v33
	v_mul_f32_e32 v34, v39, v37
	v_mul_f32_e32 v34, v35, v34
	v_cvt_pk_bf16_f32 v33, v33, v34
	v_mul_f32_e32 v34, 0xbfb8aa3b, v28
	v_exp_f32_e32 v34, v34
	v_mul_f32_e32 v35, 0xbfb8aa3b, v29
	v_exp_f32_e32 v35, v35
	global_store_dwordx2 v[48:49], v[32:33], off offset:128
	v_add_f32_e32 v34, 1.0, v34
	v_rcp_f32_e32 v34, v34
	v_add_f32_e32 v35, 1.0, v35
	v_rcp_f32_e32 v35, v35
	v_add_u32_e32 v32, 0xa0, v151
	v_mul_f32_e32 v28, v28, v34
	v_mul_f32_e32 v24, v24, v28
	v_mul_f32_e32 v28, v29, v35
	v_mul_f32_e32 v29, 0xbfb8aa3b, v30
	v_exp_f32_e32 v29, v29
	v_mul_f32_e32 v34, 0xbfb8aa3b, v31
	v_exp_f32_e32 v34, v34
	v_mul_f32_e32 v25, v25, v28
	v_add_f32_e32 v28, 1.0, v29
	v_rcp_f32_e32 v28, v28
	v_add_f32_e32 v29, 1.0, v34
	v_rcp_f32_e32 v29, v29
	v_cvt_pk_bf16_f32 v24, v24, v25
	v_mul_f32_e32 v25, v30, v28
	v_mul_f32_e32 v25, v26, v25
	v_mul_f32_e32 v26, v31, v29
	v_mul_f32_e32 v26, v27, v26
	v_mul_f32_e32 v27, 0xbfb8aa3b, v20
	v_exp_f32_e32 v27, v27
	v_mul_f32_e32 v28, 0xbfb8aa3b, v21
	v_exp_f32_e32 v28, v28
	v_cvt_pk_bf16_f32 v25, v25, v26
	v_add_f32_e32 v26, 1.0, v27
	v_rcp_f32_e32 v26, v26
	v_add_f32_e32 v27, 1.0, v28
	v_rcp_f32_e32 v27, v27
	v_mad_i64_i32 v[32:33], s[26:27], v32, s55, v[144:145]
	v_lshl_add_u64 v[32:33], v[32:33], 0, s[24:25]
	v_lshl_add_u64 v[32:33], v[32:33], 0, s[12:13]
	v_mul_f32_e32 v20, v20, v26
	v_lshl_add_u64 v[32:33], v[32:33], 0, v[136:137]
	v_mul_f32_e32 v16, v16, v20
	v_mul_f32_e32 v20, v21, v27
	v_mul_f32_e32 v21, 0xbfb8aa3b, v22
	global_store_dwordx2 v[32:33], v[24:25], off
	v_exp_f32_e32 v21, v21
	v_mul_f32_e32 v24, 0xbfb8aa3b, v23
	v_exp_f32_e32 v24, v24
	v_mul_f32_e32 v17, v17, v20
	v_add_f32_e32 v20, 1.0, v21
	v_rcp_f32_e32 v20, v20
	v_add_f32_e32 v21, 1.0, v24
	v_rcp_f32_e32 v21, v21
	v_cvt_pk_bf16_f32 v16, v16, v17
	v_mul_f32_e32 v17, v22, v20
	v_mul_f32_e32 v17, v18, v17
	v_mul_f32_e32 v18, v23, v21
	v_mul_f32_e32 v18, v19, v18
	v_cvt_pk_bf16_f32 v17, v17, v18
	v_mul_f32_e32 v18, 0xbfb8aa3b, v12
	v_exp_f32_e32 v18, v18
	v_mul_f32_e32 v19, 0xbfb8aa3b, v13
	v_exp_f32_e32 v19, v19
	global_store_dwordx2 v[32:33], v[16:17], off offset:128
	v_add_f32_e32 v18, 1.0, v18
	v_rcp_f32_e32 v18, v18
	v_add_f32_e32 v19, 1.0, v19
	v_rcp_f32_e32 v19, v19
	v_add_u32_e32 v16, 0xb0, v151
	v_mul_f32_e32 v12, v12, v18
	v_mul_f32_e32 v8, v8, v12
	v_mul_f32_e32 v12, v13, v19
	v_mul_f32_e32 v13, 0xbfb8aa3b, v14
	v_exp_f32_e32 v13, v13
	v_mul_f32_e32 v18, 0xbfb8aa3b, v15
	v_exp_f32_e32 v18, v18
	v_mul_f32_e32 v9, v9, v12
	v_add_f32_e32 v12, 1.0, v13
	v_rcp_f32_e32 v12, v12
	v_add_f32_e32 v13, 1.0, v18
	v_rcp_f32_e32 v13, v13
	v_cvt_pk_bf16_f32 v8, v8, v9
	v_mul_f32_e32 v9, v14, v12
	v_mul_f32_e32 v9, v10, v9
	v_mul_f32_e32 v10, v15, v13
	v_mul_f32_e32 v10, v11, v10
	v_mul_f32_e32 v11, 0xbfb8aa3b, v4
	v_exp_f32_e32 v11, v11
	v_mul_f32_e32 v12, 0xbfb8aa3b, v5
	v_exp_f32_e32 v12, v12
	v_cvt_pk_bf16_f32 v9, v9, v10
	v_add_f32_e32 v10, 1.0, v11
	v_rcp_f32_e32 v10, v10
	v_add_f32_e32 v11, 1.0, v12
	v_rcp_f32_e32 v11, v11
	v_mad_i64_i32 v[16:17], s[26:27], v16, s55, v[144:145]
	v_lshl_add_u64 v[16:17], v[16:17], 0, s[24:25]
	v_lshl_add_u64 v[16:17], v[16:17], 0, s[12:13]
	v_mul_f32_e32 v4, v4, v10
	v_lshl_add_u64 v[16:17], v[16:17], 0, v[136:137]
	v_mul_f32_e32 v0, v0, v4
	v_mul_f32_e32 v4, v5, v11
	v_mul_f32_e32 v5, 0xbfb8aa3b, v6
	global_store_dwordx2 v[16:17], v[8:9], off
	v_exp_f32_e32 v5, v5
	v_mul_f32_e32 v8, 0xbfb8aa3b, v7
	v_exp_f32_e32 v8, v8
	v_mul_f32_e32 v1, v1, v4
	v_add_f32_e32 v4, 1.0, v5
	v_rcp_f32_e32 v4, v4
	v_add_f32_e32 v5, 1.0, v8
	v_rcp_f32_e32 v5, v5
	v_cvt_pk_bf16_f32 v0, v0, v1
	v_mul_f32_e32 v1, v6, v4
	v_mul_f32_e32 v1, v2, v1
	v_mul_f32_e32 v2, v7, v5
	s_and_b64 vcc, exec, s[18:19]
	s_mov_b32 s13, s16
	s_mov_b32 s24, s14
	s_mov_b64 s[28:29], s[22:23]
	s_mov_b64 s[26:27], s[20:21]
	v_mul_f32_e32 v2, v3, v2
	v_cvt_pk_bf16_f32 v1, v1, v2
	global_store_dwordx2 v[16:17], v[0:1], off offset:128
	s_cbranch_vccz .LBB0_1062
	s_waitcnt vmcnt(0)
	s_cmpk_gt_u32 s2, 0xff
	s_cbranch_scc1 .LBB0_1069
	s_barrier

.LBB0_1156:
	s_and_b64 vcc, exec, s[2:3]
	s_cbranch_vccnz .Lq3_p9_one
	.p2align 7
.Lq3_p9_two:
	ds_read_b128 v[96:99], v189
	ds_read_b128 v[100:103], v189 offset:1024
	ds_read_b128 v[104:107], v189 offset:2048
	ds_read_b128 v[108:111], v189 offset:3072
	s_mov_b32 m0, s68
	ds_read_b128 v[144:147], v190
	ds_read_b128 v[148:151], v190 offset:1024
	ds_read_b128 v[136:139], v190 offset:2048
	global_load_lds_dwordx4 v162, s[4:5]
	s_add_i32 m0, s43, 0xe000
	ds_read_b128 v[140:143], v190 offset:3072
	ds_read_b128 v[128:131], v190 offset:4096
	ds_read_b128 v[132:135], v190 offset:5120
	global_load_lds_dwordx4 v164, s[4:5]
	s_add_u32 s4, s4, 0x100
	s_addc_u32 s5, s5, 0
	s_cmpk_eq_i32 s71, 0x54
	s_cselect_b32 s37, s25, s5
	s_cselect_b32 s36, s24, s4
	s_cselect_b32 s31, s7, s29
	s_cselect_b32 s30, s6, s28
	s_waitcnt lgkmcnt(8)
	s_barrier
	s_waitcnt lgkmcnt(0)
	v_mfma_f32_16x16x32_bf16 v[92:95], v[96:99], v[144:147], v[92:95]
	v_mfma_f32_16x16x32_bf16 v[88:91], v[104:107], v[144:147], v[88:91]
	v_mfma_f32_16x16x32_bf16 v[76:79], v[96:99], v[136:139], v[76:79]
	v_mfma_f32_16x16x32_bf16 v[72:75], v[104:107], v[136:139], v[72:75]
	v_mfma_f32_16x16x32_bf16 v[60:63], v[96:99], v[128:131], v[60:63]
	v_mfma_f32_16x16x32_bf16 v[56:59], v[104:107], v[128:131], v[56:59]
	v_mfma_f32_16x16x32_bf16 v[92:95], v[100:103], v[148:151], v[92:95]
	v_mfma_f32_16x16x32_bf16 v[88:91], v[108:111], v[148:151], v[88:91]
	v_mfma_f32_16x16x32_bf16 v[76:79], v[100:103], v[140:143], v[76:79]
	v_mfma_f32_16x16x32_bf16 v[72:75], v[108:111], v[140:143], v[72:75]
	v_mfma_f32_16x16x32_bf16 v[60:63], v[100:103], v[132:135], v[60:63]
	v_mfma_f32_16x16x32_bf16 v[56:59], v[108:111], v[132:135], v[56:59]
	s_barrier
	v_add_u32_e32 v124, 0x14000, v188
	s_mov_b32 m0, s46
	ds_read_b128 v[112:115], v124
	ds_read_b128 v[116:119], v124 offset:1024
	global_load_lds_dwordx4 v152, s[30:31]
	s_mov_b32 m0, s47
	ds_read_b128 v[120:123], v124 offset:2048
	ds_read_b128 v[124:127], v124 offset:3072
	global_load_lds_dwordx4 v154, s[30:31]
	s_barrier
	s_waitcnt lgkmcnt(0)
	v_mfma_f32_16x16x32_bf16 v[84:87], v[112:115], v[144:147], v[84:87]
	v_mfma_f32_16x16x32_bf16 v[80:83], v[120:123], v[144:147], v[80:83]
	v_mfma_f32_16x16x32_bf16 v[68:71], v[112:115], v[136:139], v[68:71]
	v_mfma_f32_16x16x32_bf16 v[64:67], v[120:123], v[136:139], v[64:67]
	v_mfma_f32_16x16x32_bf16 v[52:55], v[112:115], v[128:131], v[52:55]
	v_mfma_f32_16x16x32_bf16 v[48:51], v[120:123], v[128:131], v[48:51]
	v_mfma_f32_16x16x32_bf16 v[84:87], v[116:119], v[148:151], v[84:87]
	v_mfma_f32_16x16x32_bf16 v[80:83], v[124:127], v[148:151], v[80:83]
	v_mfma_f32_16x16x32_bf16 v[68:71], v[116:119], v[140:143], v[68:71]
	v_mfma_f32_16x16x32_bf16 v[64:67], v[124:127], v[140:143], v[64:67]
	v_mfma_f32_16x16x32_bf16 v[52:55], v[116:119], v[132:135], v[52:55]
	v_mfma_f32_16x16x32_bf16 v[48:51], v[124:127], v[132:135], v[48:51]
	s_barrier
	s_mov_b32 m0, s43
	ds_read_b128 v[144:147], v190 offset:16384
	ds_read_b128 v[148:151], v190 offset:17408
	ds_read_b128 v[136:139], v190 offset:18432
	global_load_lds_dwordx4 v152, s[36:37]
	s_add_i32 m0, s43, 0x2000
	ds_read_b128 v[140:143], v190 offset:19456
	ds_read_b128 v[128:131], v190 offset:20480
	ds_read_b128 v[132:135], v190 offset:21504
	global_load_lds_dwordx4 v154, s[36:37]
	s_barrier
	s_waitcnt lgkmcnt(0)
	v_mfma_f32_16x16x32_bf16 v[44:47], v[96:99], v[144:147], v[44:47]
	v_mfma_f32_16x16x32_bf16 v[40:43], v[104:107], v[144:147], v[40:43]
	v_mfma_f32_16x16x32_bf16 v[28:31], v[96:99], v[136:139], v[28:31]
	v_mfma_f32_16x16x32_bf16 v[24:27], v[104:107], v[136:139], v[24:27]
	v_mfma_f32_16x16x32_bf16 v[12:15], v[96:99], v[128:131], v[12:15]
	v_mfma_f32_16x16x32_bf16 v[8:11], v[104:107], v[128:131], v[8:11]
	v_mfma_f32_16x16x32_bf16 v[44:47], v[100:103], v[148:151], v[44:47]
	v_mfma_f32_16x16x32_bf16 v[40:43], v[108:111], v[148:151], v[40:43]
	v_mfma_f32_16x16x32_bf16 v[28:31], v[100:103], v[140:143], v[28:31]
	v_mfma_f32_16x16x32_bf16 v[24:27], v[108:111], v[140:143], v[24:27]
	v_mfma_f32_16x16x32_bf16 v[12:15], v[100:103], v[132:135], v[12:15]
	v_mfma_f32_16x16x32_bf16 v[8:11], v[108:111], v[132:135], v[8:11]
	s_barrier
	s_add_u32 s34, s30, 0x160000
	s_addc_u32 s35, s31, 0
	s_mov_b32 m0, s48
	s_nop 0
	global_load_lds_dwordx4 v152, s[34:35]
	s_mov_b32 m0, s49
	s_nop 0
	global_load_lds_dwordx4 v154, s[34:35]
	s_waitcnt vmcnt(6)
	s_barrier
	v_mfma_f32_16x16x32_bf16 v[36:39], v[112:115], v[144:147], v[36:39]
	v_mfma_f32_16x16x32_bf16 v[32:35], v[120:123], v[144:147], v[32:35]
	v_mfma_f32_16x16x32_bf16 v[20:23], v[112:115], v[136:139], v[20:23]
	v_mfma_f32_16x16x32_bf16 v[16:19], v[120:123], v[136:139], v[16:19]
	v_mfma_f32_16x16x32_bf16 v[4:7], v[112:115], v[128:131], v[4:7]
	v_mfma_f32_16x16x32_bf16 v[0:3], v[120:123], v[128:131], v[0:3]
	v_mfma_f32_16x16x32_bf16 v[36:39], v[116:119], v[148:151], v[36:39]
	v_mfma_f32_16x16x32_bf16 v[32:35], v[124:127], v[148:151], v[32:35]
	v_mfma_f32_16x16x32_bf16 v[20:23], v[116:119], v[140:143], v[20:23]
	v_mfma_f32_16x16x32_bf16 v[16:19], v[124:127], v[140:143], v[16:19]
	v_mfma_f32_16x16x32_bf16 v[4:7], v[116:119], v[132:135], v[4:7]
	v_mfma_f32_16x16x32_bf16 v[0:3], v[124:127], v[132:135], v[0:3]
	s_barrier
	v_add_u32_e32 v96, 0x18000, v188
	ds_read_b128 v[112:115], v96
	ds_read_b128 v[116:119], v96 offset:1024
	ds_read_b128 v[120:123], v96 offset:2048
	ds_read_b128 v[124:127], v96 offset:3072
	s_add_u32 s36, s36, 0x108000
	s_addc_u32 s37, s37, 0
	s_mov_b32 m0, s50
	ds_read_b128 v[144:147], v190 offset:32768
	ds_read_b128 v[148:151], v190 offset:33792
	ds_read_b128 v[136:139], v190 offset:34816
	global_load_lds_dwordx4 v152, s[36:37]
	s_add_i32 m0, s43, 0x6000
	ds_read_b128 v[140:143], v190 offset:35840
	ds_read_b128 v[128:131], v190 offset:36864
	ds_read_b128 v[132:135], v190 offset:37888
	global_load_lds_dwordx4 v154, s[36:37]
	s_waitcnt lgkmcnt(8)
	s_barrier
	s_waitcnt lgkmcnt(0)
	v_mfma_f32_16x16x32_bf16 v[92:95], v[112:115], v[144:147], v[92:95]
	v_mfma_f32_16x16x32_bf16 v[88:91], v[120:123], v[144:147], v[88:91]
	v_mfma_f32_16x16x32_bf16 v[76:79], v[112:115], v[136:139], v[76:79]
	v_mfma_f32_16x16x32_bf16 v[72:75], v[120:123], v[136:139], v[72:75]
	v_mfma_f32_16x16x32_bf16 v[60:63], v[112:115], v[128:131], v[60:63]
	v_mfma_f32_16x16x32_bf16 v[56:59], v[120:123], v[128:131], v[56:59]
	v_mfma_f32_16x16x32_bf16 v[92:95], v[116:119], v[148:151], v[92:95]
	v_mfma_f32_16x16x32_bf16 v[88:91], v[124:127], v[148:151], v[88:91]
	v_mfma_f32_16x16x32_bf16 v[76:79], v[116:119], v[140:143], v[76:79]
	v_mfma_f32_16x16x32_bf16 v[72:75], v[124:127], v[140:143], v[72:75]
	v_mfma_f32_16x16x32_bf16 v[60:63], v[116:119], v[132:135], v[60:63]
	v_mfma_f32_16x16x32_bf16 v[56:59], v[124:127], v[132:135], v[56:59]
	s_barrier
	v_add_u32_e32 v108, 0x1c000, v188
	s_add_u32 s34, s30, 0x80
	s_addc_u32 s35, s31, 0
	s_mov_b32 m0, s51
	ds_read_b128 v[96:99], v108
	ds_read_b128 v[100:103], v108 offset:1024
	global_load_lds_dwordx4 v152, s[34:35]
	s_mov_b32 m0, s52
	ds_read_b128 v[104:107], v108 offset:2048
	ds_read_b128 v[108:111], v108 offset:3072
	global_load_lds_dwordx4 v154, s[34:35]
	s_barrier
	s_waitcnt lgkmcnt(0)
	v_mfma_f32_16x16x32_bf16 v[84:87], v[96:99], v[144:147], v[84:87]
	v_mfma_f32_16x16x32_bf16 v[80:83], v[104:107], v[144:147], v[80:83]
	v_mfma_f32_16x16x32_bf16 v[68:71], v[96:99], v[136:139], v[68:71]
	v_mfma_f32_16x16x32_bf16 v[64:67], v[104:107], v[136:139], v[64:67]
	v_mfma_f32_16x16x32_bf16 v[52:55], v[96:99], v[128:131], v[52:55]
	v_mfma_f32_16x16x32_bf16 v[48:51], v[104:107], v[128:131], v[48:51]
	v_mfma_f32_16x16x32_bf16 v[84:87], v[100:103], v[148:151], v[84:87]
	v_mfma_f32_16x16x32_bf16 v[80:83], v[108:111], v[148:151], v[80:83]
	v_mfma_f32_16x16x32_bf16 v[68:71], v[100:103], v[140:143], v[68:71]
	v_mfma_f32_16x16x32_bf16 v[64:67], v[108:111], v[140:143], v[64:67]
	v_mfma_f32_16x16x32_bf16 v[52:55], v[100:103], v[132:135], v[52:55]
	v_mfma_f32_16x16x32_bf16 v[48:51], v[108:111], v[132:135], v[48:51]
	s_barrier
	s_add_u32 s34, s36, 0xffef8080
	s_addc_u32 s35, s37, -1
	s_mov_b32 m0, s53
	ds_read_b128 v[144:147], v190 offset:49152
	ds_read_b128 v[148:151], v190 offset:50176
	ds_read_b128 v[136:139], v190 offset:51200
	global_load_lds_dwordx4 v152, s[34:35]
	s_add_i32 m0, s43, 0xa000
	ds_read_b128 v[140:143], v190 offset:52224
	ds_read_b128 v[128:131], v190 offset:53248
	ds_read_b128 v[132:135], v190 offset:54272
	global_load_lds_dwordx4 v154, s[34:35]
	s_barrier
	s_waitcnt lgkmcnt(0)
	v_mfma_f32_16x16x32_bf16 v[44:47], v[112:115], v[144:147], v[44:47]
	v_mfma_f32_16x16x32_bf16 v[40:43], v[120:123], v[144:147], v[40:43]
	v_mfma_f32_16x16x32_bf16 v[28:31], v[112:115], v[136:139], v[28:31]
	v_mfma_f32_16x16x32_bf16 v[24:27], v[120:123], v[136:139], v[24:27]
	v_mfma_f32_16x16x32_bf16 v[12:15], v[112:115], v[128:131], v[12:15]
	v_mfma_f32_16x16x32_bf16 v[8:11], v[120:123], v[128:131], v[8:11]
	v_mfma_f32_16x16x32_bf16 v[44:47], v[116:119], v[148:151], v[44:47]
	v_mfma_f32_16x16x32_bf16 v[40:43], v[124:127], v[148:151], v[40:43]
	v_mfma_f32_16x16x32_bf16 v[28:31], v[116:119], v[140:143], v[28:31]
	v_mfma_f32_16x16x32_bf16 v[24:27], v[124:127], v[140:143], v[24:27]
	v_mfma_f32_16x16x32_bf16 v[12:15], v[116:119], v[132:135], v[12:15]
	v_mfma_f32_16x16x32_bf16 v[8:11], v[124:127], v[132:135], v[8:11]
	s_barrier
	s_add_u32 s34, s30, 0x160080
	s_addc_u32 s35, s31, 0
	s_mov_b32 m0, s54
	s_add_i32 s71, s71, 2
	global_load_lds_dwordx4 v152, s[34:35]
	s_mov_b32 m0, s55
	s_nop 0
	global_load_lds_dwordx4 v154, s[34:35]
	s_add_u32 s28, s28, 0x100
	s_addc_u32 s29, s29, 0
	s_waitcnt vmcnt(6)
	s_barrier
	v_mfma_f32_16x16x32_bf16 v[36:39], v[96:99], v[144:147], v[36:39]
	v_mfma_f32_16x16x32_bf16 v[32:35], v[104:107], v[144:147], v[32:35]
	v_mfma_f32_16x16x32_bf16 v[20:23], v[96:99], v[136:139], v[20:23]
	v_mfma_f32_16x16x32_bf16 v[16:19], v[104:107], v[136:139], v[16:19]
	v_mfma_f32_16x16x32_bf16 v[4:7], v[96:99], v[128:131], v[4:7]
	v_mfma_f32_16x16x32_bf16 v[0:3], v[104:107], v[128:131], v[0:3]
	v_mfma_f32_16x16x32_bf16 v[36:39], v[100:103], v[148:151], v[36:39]
	v_mfma_f32_16x16x32_bf16 v[32:35], v[108:111], v[148:151], v[32:35]
	v_mfma_f32_16x16x32_bf16 v[20:23], v[100:103], v[140:143], v[20:23]
	v_mfma_f32_16x16x32_bf16 v[16:19], v[108:111], v[140:143], v[16:19]
	v_mfma_f32_16x16x32_bf16 v[4:7], v[100:103], v[132:135], v[4:7]
	v_mfma_f32_16x16x32_bf16 v[0:3], v[108:111], v[132:135], v[0:3]
	s_cmpk_gt_u32 s71, 0x55
	s_barrier
	s_cbranch_scc0 .Lq3_p9_two
	s_branch .LBB0_1172
	.p2align 7
.Lq3_p9_one:
	ds_read_b128 v[96:99], v189
	ds_read_b128 v[100:103], v189 offset:1024
	ds_read_b128 v[104:107], v189 offset:2048
	ds_read_b128 v[108:111], v189 offset:3072
	s_mov_b32 m0, s68
	ds_read_b128 v[144:147], v190
	ds_read_b128 v[148:151], v190 offset:1024
	ds_read_b128 v[136:139], v190 offset:2048
	global_load_lds_dwordx4 v162, s[4:5]
	ds_read_b128 v[140:143], v190 offset:3072
	ds_read_b128 v[128:131], v190 offset:4096
	ds_read_b128 v[132:135], v190 offset:5120
	s_add_u32 s4, s4, 0x100
	s_addc_u32 s5, s5, 0
	s_cmpk_eq_i32 s71, 0x54
	s_cselect_b32 s37, s25, s5
	s_cselect_b32 s36, s24, s4
	s_cselect_b32 s31, s7, s29
	s_cselect_b32 s30, s6, s28
	s_waitcnt lgkmcnt(8)
	s_barrier
	s_waitcnt lgkmcnt(0)
	v_mfma_f32_16x16x32_bf16 v[92:95], v[96:99], v[144:147], v[92:95]
	v_mfma_f32_16x16x32_bf16 v[88:91], v[104:107], v[144:147], v[88:91]
	v_mfma_f32_16x16x32_bf16 v[76:79], v[96:99], v[136:139], v[76:79]
	v_mfma_f32_16x16x32_bf16 v[72:75], v[104:107], v[136:139], v[72:75]
	v_mfma_f32_16x16x32_bf16 v[60:63], v[96:99], v[128:131], v[60:63]
	v_mfma_f32_16x16x32_bf16 v[56:59], v[104:107], v[128:131], v[56:59]
	v_mfma_f32_16x16x32_bf16 v[92:95], v[100:103], v[148:151], v[92:95]
	v_mfma_f32_16x16x32_bf16 v[88:91], v[108:111], v[148:151], v[88:91]
	v_mfma_f32_16x16x32_bf16 v[76:79], v[100:103], v[140:143], v[76:79]
	v_mfma_f32_16x16x32_bf16 v[72:75], v[108:111], v[140:143], v[72:75]
	v_mfma_f32_16x16x32_bf16 v[60:63], v[100:103], v[132:135], v[60:63]
	v_mfma_f32_16x16x32_bf16 v[56:59], v[108:111], v[132:135], v[56:59]
	s_barrier
	v_add_u32_e32 v124, 0x14000, v188
	s_mov_b32 m0, s46
	ds_read_b128 v[112:115], v124
	ds_read_b128 v[116:119], v124 offset:1024
	global_load_lds_dwordx4 v152, s[30:31]
	s_mov_b32 m0, s47
	ds_read_b128 v[120:123], v124 offset:2048
	ds_read_b128 v[124:127], v124 offset:3072
	global_load_lds_dwordx4 v154, s[30:31]
	s_barrier
	s_waitcnt lgkmcnt(0)
	v_mfma_f32_16x16x32_bf16 v[84:87], v[112:115], v[144:147], v[84:87]
	v_mfma_f32_16x16x32_bf16 v[80:83], v[120:123], v[144:147], v[80:83]
	v_mfma_f32_16x16x32_bf16 v[68:71], v[112:115], v[136:139], v[68:71]
	v_mfma_f32_16x16x32_bf16 v[64:67], v[120:123], v[136:139], v[64:67]
	v_mfma_f32_16x16x32_bf16 v[52:55], v[112:115], v[128:131], v[52:55]
	v_mfma_f32_16x16x32_bf16 v[48:51], v[120:123], v[128:131], v[48:51]
	v_mfma_f32_16x16x32_bf16 v[84:87], v[116:119], v[148:151], v[84:87]
	v_mfma_f32_16x16x32_bf16 v[80:83], v[124:127], v[148:151], v[80:83]
	v_mfma_f32_16x16x32_bf16 v[68:71], v[116:119], v[140:143], v[68:71]
	v_mfma_f32_16x16x32_bf16 v[64:67], v[124:127], v[140:143], v[64:67]
	v_mfma_f32_16x16x32_bf16 v[52:55], v[116:119], v[132:135], v[52:55]
	v_mfma_f32_16x16x32_bf16 v[48:51], v[124:127], v[132:135], v[48:51]
	s_barrier
	s_mov_b32 m0, s43
	ds_read_b128 v[144:147], v190 offset:16384
	ds_read_b128 v[148:151], v190 offset:17408
	ds_read_b128 v[136:139], v190 offset:18432
	global_load_lds_dwordx4 v152, s[36:37]
	ds_read_b128 v[140:143], v190 offset:19456
	ds_read_b128 v[128:131], v190 offset:20480
	ds_read_b128 v[132:135], v190 offset:21504
	s_barrier
	s_waitcnt lgkmcnt(0)
	v_mfma_f32_16x16x32_bf16 v[44:47], v[96:99], v[144:147], v[44:47]
	v_mfma_f32_16x16x32_bf16 v[40:43], v[104:107], v[144:147], v[40:43]
	v_mfma_f32_16x16x32_bf16 v[28:31], v[96:99], v[136:139], v[28:31]
	v_mfma_f32_16x16x32_bf16 v[24:27], v[104:107], v[136:139], v[24:27]
	v_mfma_f32_16x16x32_bf16 v[12:15], v[96:99], v[128:131], v[12:15]
	v_mfma_f32_16x16x32_bf16 v[8:11], v[104:107], v[128:131], v[8:11]
	v_mfma_f32_16x16x32_bf16 v[44:47], v[100:103], v[148:151], v[44:47]
	v_mfma_f32_16x16x32_bf16 v[40:43], v[108:111], v[148:151], v[40:43]
	v_mfma_f32_16x16x32_bf16 v[28:31], v[100:103], v[140:143], v[28:31]
	v_mfma_f32_16x16x32_bf16 v[24:27], v[108:111], v[140:143], v[24:27]
	v_mfma_f32_16x16x32_bf16 v[12:15], v[100:103], v[132:135], v[12:15]
	v_mfma_f32_16x16x32_bf16 v[8:11], v[108:111], v[132:135], v[8:11]
	s_barrier
	s_add_u32 s34, s30, 0x160000
	s_addc_u32 s35, s31, 0
	s_mov_b32 m0, s48
	s_nop 0
	global_load_lds_dwordx4 v152, s[34:35]
	s_mov_b32 m0, s49
	s_nop 0
	global_load_lds_dwordx4 v154, s[34:35]
	s_waitcnt vmcnt(5)
	s_barrier
	v_mfma_f32_16x16x32_bf16 v[36:39], v[112:115], v[144:147], v[36:39]
	v_mfma_f32_16x16x32_bf16 v[32:35], v[120:123], v[144:147], v[32:35]
	v_mfma_f32_16x16x32_bf16 v[20:23], v[112:115], v[136:139], v[20:23]
	v_mfma_f32_16x16x32_bf16 v[16:19], v[120:123], v[136:139], v[16:19]
	v_mfma_f32_16x16x32_bf16 v[4:7], v[112:115], v[128:131], v[4:7]
	v_mfma_f32_16x16x32_bf16 v[0:3], v[120:123], v[128:131], v[0:3]
	v_mfma_f32_16x16x32_bf16 v[36:39], v[116:119], v[148:151], v[36:39]
	v_mfma_f32_16x16x32_bf16 v[32:35], v[124:127], v[148:151], v[32:35]
	v_mfma_f32_16x16x32_bf16 v[20:23], v[116:119], v[140:143], v[20:23]
	v_mfma_f32_16x16x32_bf16 v[16:19], v[124:127], v[140:143], v[16:19]
	v_mfma_f32_16x16x32_bf16 v[4:7], v[116:119], v[132:135], v[4:7]
	v_mfma_f32_16x16x32_bf16 v[0:3], v[124:127], v[132:135], v[0:3]
	s_barrier
	v_add_u32_e32 v96, 0x18000, v188
	ds_read_b128 v[112:115], v96
	ds_read_b128 v[116:119], v96 offset:1024
	ds_read_b128 v[120:123], v96 offset:2048
	ds_read_b128 v[124:127], v96 offset:3072
	s_add_u32 s36, s36, 0x108000
	s_addc_u32 s37, s37, 0
	s_mov_b32 m0, s50
	ds_read_b128 v[144:147], v190 offset:32768
	ds_read_b128 v[148:151], v190 offset:33792
	ds_read_b128 v[136:139], v190 offset:34816
	global_load_lds_dwordx4 v152, s[36:37]
	ds_read_b128 v[140:143], v190 offset:35840
	ds_read_b128 v[128:131], v190 offset:36864
	ds_read_b128 v[132:135], v190 offset:37888
	s_waitcnt lgkmcnt(8)
	s_barrier
	s_waitcnt lgkmcnt(0)
	v_mfma_f32_16x16x32_bf16 v[92:95], v[112:115], v[144:147], v[92:95]
	v_mfma_f32_16x16x32_bf16 v[88:91], v[120:123], v[144:147], v[88:91]
	v_mfma_f32_16x16x32_bf16 v[76:79], v[112:115], v[136:139], v[76:79]
	v_mfma_f32_16x16x32_bf16 v[72:75], v[120:123], v[136:139], v[72:75]
	v_mfma_f32_16x16x32_bf16 v[60:63], v[112:115], v[128:131], v[60:63]
	v_mfma_f32_16x16x32_bf16 v[56:59], v[120:123], v[128:131], v[56:59]
	v_mfma_f32_16x16x32_bf16 v[92:95], v[116:119], v[148:151], v[92:95]
	v_mfma_f32_16x16x32_bf16 v[88:91], v[124:127], v[148:151], v[88:91]
	v_mfma_f32_16x16x32_bf16 v[76:79], v[116:119], v[140:143], v[76:79]
	v_mfma_f32_16x16x32_bf16 v[72:75], v[124:127], v[140:143], v[72:75]
	v_mfma_f32_16x16x32_bf16 v[60:63], v[116:119], v[132:135], v[60:63]
	v_mfma_f32_16x16x32_bf16 v[56:59], v[124:127], v[132:135], v[56:59]
	s_barrier
	v_add_u32_e32 v108, 0x1c000, v188
	s_add_u32 s34, s30, 0x80
	s_addc_u32 s35, s31, 0
	s_mov_b32 m0, s51
	ds_read_b128 v[96:99], v108
	ds_read_b128 v[100:103], v108 offset:1024
	global_load_lds_dwordx4 v152, s[34:35]
	s_mov_b32 m0, s52
	ds_read_b128 v[104:107], v108 offset:2048
	ds_read_b128 v[108:111], v108 offset:3072
	global_load_lds_dwordx4 v154, s[34:35]
	s_barrier
	s_waitcnt lgkmcnt(0)
	v_mfma_f32_16x16x32_bf16 v[84:87], v[96:99], v[144:147], v[84:87]
	v_mfma_f32_16x16x32_bf16 v[80:83], v[104:107], v[144:147], v[80:83]
	v_mfma_f32_16x16x32_bf16 v[68:71], v[96:99], v[136:139], v[68:71]
	v_mfma_f32_16x16x32_bf16 v[64:67], v[104:107], v[136:139], v[64:67]
	v_mfma_f32_16x16x32_bf16 v[52:55], v[96:99], v[128:131], v[52:55]
	v_mfma_f32_16x16x32_bf16 v[48:51], v[104:107], v[128:131], v[48:51]
	v_mfma_f32_16x16x32_bf16 v[84:87], v[100:103], v[148:151], v[84:87]
	v_mfma_f32_16x16x32_bf16 v[80:83], v[108:111], v[148:151], v[80:83]
	v_mfma_f32_16x16x32_bf16 v[68:71], v[100:103], v[140:143], v[68:71]
	v_mfma_f32_16x16x32_bf16 v[64:67], v[108:111], v[140:143], v[64:67]
	v_mfma_f32_16x16x32_bf16 v[52:55], v[100:103], v[132:135], v[52:55]
	v_mfma_f32_16x16x32_bf16 v[48:51], v[108:111], v[132:135], v[48:51]
	s_barrier
	s_add_u32 s34, s36, 0xffef8080
	s_addc_u32 s35, s37, -1
	s_mov_b32 m0, s53
	ds_read_b128 v[144:147], v190 offset:49152
	ds_read_b128 v[148:151], v190 offset:50176
	ds_read_b128 v[136:139], v190 offset:51200
	global_load_lds_dwordx4 v152, s[34:35]
	ds_read_b128 v[140:143], v190 offset:52224
	ds_read_b128 v[128:131], v190 offset:53248
	ds_read_b128 v[132:135], v190 offset:54272
	s_barrier
	s_waitcnt lgkmcnt(0)
	v_mfma_f32_16x16x32_bf16 v[44:47], v[112:115], v[144:147], v[44:47]
	v_mfma_f32_16x16x32_bf16 v[40:43], v[120:123], v[144:147], v[40:43]
	v_mfma_f32_16x16x32_bf16 v[28:31], v[112:115], v[136:139], v[28:31]
	v_mfma_f32_16x16x32_bf16 v[24:27], v[120:123], v[136:139], v[24:27]
	v_mfma_f32_16x16x32_bf16 v[12:15], v[112:115], v[128:131], v[12:15]
	v_mfma_f32_16x16x32_bf16 v[8:11], v[120:123], v[128:131], v[8:11]
	v_mfma_f32_16x16x32_bf16 v[44:47], v[116:119], v[148:151], v[44:47]
	v_mfma_f32_16x16x32_bf16 v[40:43], v[124:127], v[148:151], v[40:43]
	v_mfma_f32_16x16x32_bf16 v[28:31], v[116:119], v[140:143], v[28:31]
	v_mfma_f32_16x16x32_bf16 v[24:27], v[124:127], v[140:143], v[24:27]
	v_mfma_f32_16x16x32_bf16 v[12:15], v[116:119], v[132:135], v[12:15]
	v_mfma_f32_16x16x32_bf16 v[8:11], v[124:127], v[132:135], v[8:11]
	s_barrier
	s_add_u32 s34, s30, 0x160080
	s_addc_u32 s35, s31, 0
	s_mov_b32 m0, s54
	s_add_i32 s71, s71, 2
	global_load_lds_dwordx4 v152, s[34:35]
	s_mov_b32 m0, s55
	s_nop 0
	global_load_lds_dwordx4 v154, s[34:35]
	s_add_u32 s28, s28, 0x100
	s_addc_u32 s29, s29, 0
	s_waitcnt vmcnt(5)
	s_barrier
	v_mfma_f32_16x16x32_bf16 v[36:39], v[96:99], v[144:147], v[36:39]
	v_mfma_f32_16x16x32_bf16 v[32:35], v[104:107], v[144:147], v[32:35]
	v_mfma_f32_16x16x32_bf16 v[20:23], v[96:99], v[136:139], v[20:23]
	v_mfma_f32_16x16x32_bf16 v[16:19], v[104:107], v[136:139], v[16:19]
	v_mfma_f32_16x16x32_bf16 v[4:7], v[96:99], v[128:131], v[4:7]
	v_mfma_f32_16x16x32_bf16 v[0:3], v[104:107], v[128:131], v[0:3]
	v_mfma_f32_16x16x32_bf16 v[36:39], v[100:103], v[148:151], v[36:39]
	v_mfma_f32_16x16x32_bf16 v[32:35], v[108:111], v[148:151], v[32:35]
	v_mfma_f32_16x16x32_bf16 v[20:23], v[100:103], v[140:143], v[20:23]
	v_mfma_f32_16x16x32_bf16 v[16:19], v[108:111], v[140:143], v[16:19]
	v_mfma_f32_16x16x32_bf16 v[4:7], v[100:103], v[132:135], v[4:7]
	v_mfma_f32_16x16x32_bf16 v[0:3], v[108:111], v[132:135], v[0:3]
	s_cmpk_gt_u32 s71, 0x55
	s_barrier
	s_cbranch_scc0 .Lq3_p9_one
